# attention V^T LDS layout: key-group pair of a PV fragment stored adjacent (swap group bits 0/1, XOR swizzle off bit 0) so V fragments are one ds_read_b128 instead of two ds_read_b64 (diff + DSA)
# speedup vs baseline: 1.0063x; 1.0063x over previous
; #define LAS __attribute__((address_space(3)))
; __device__ __forceinline__ void dsa_attn_item(CParams& p, LAS unsigned char* lds, int b, int qb, int tid_in, int wave) {
;     ...
;     const int hd = wave & 3, qs = wave >> 2, r = lane & 31, hh = lane >> 5;
;     const int tb0 = b * SEQ; const int q0 = qb * 64 + 32 * qs;
;     for (int i = tid; i < 4 * 132; i += NTHREADS) bdl[i] = bd[i];
;     h16x8 qf[8];
; #pragma unroll
;     for (int s = 0; s < 8; ++s) qf[s] = *(const h16x8*)(proj + (size_t)(tb0 + q0 + r) * OD_N + 1536 + hd * 128 + 16 * s + 8 * hh);
;     f32x16 o[4];
; #pragma unroll
;     for (int d = 0; d < 4; ++d)
; #pragma unroll
;         for (int i = 0; i < 16; ++i) o[d][i] = 0.f;
;     float m_run = -INFINITY, l_run = 0.f;
;     const int qp = q0 + r;
;     const int vlo = r * 72 + ((hh ^ (r >> 3)) << 2), vhi = r * 72 + (((hh ^ (r >> 3)) ^ 2) << 2);
;     const unsigned long long* bmq = bm + (size_t)(tb0 + qp) * 64;
;     const LAS float* bdh = bdl + hd * 132;
;     const int nkt = qb + 1;
;     h16x8 pk[2], pv[2];
; #pragma unroll
;     for (int i = 0; i < 2; ++i) { const int key = i * 32 + (tid >> 4), ch = tid & 15;
;         pk[i] = *(const h16x8*)(proj + (size_t)(tb0 + key) * OD_N + 2048 + ch * 8);
;         pv[i] = *(const h16x8*)(proj + (size_t)(tb0 + key) * OD_N + 2176 + ch * 8); }
;     ATT_STAGE(0, 2048, 2176, 1);
;     unsigned long long mkn = bmq[0];
;     __syncthreads();
.LBB0_510:
	s_or_b64 exec, exec, s[4:5]
	v_add_u32_e32 v145, s84, v183
	v_and_b32_e32 v80, 31, v16
	v_add_u32_e32 v0, s58, v145
	v_bfe_u32 v81, v16, 5, 1
	v_or_b32_e32 v144, v80, v0
	v_mad_i64_i32 v[2:3], s[4:5], v144, s33, v[142:143]
	v_lshlrev_b32_e32 v0, 4, v81
	v_lshl_add_u64 v[34:35], v[2:3], 0, v[0:1]
	v_or_b32_e32 v0, v80, v145
	v_add_u32_e32 v14, s58, v0
	v_ashrrev_i32_e32 v17, 4, v16
	v_lshlrev_b32_e32 v0, 3, v16
	v_add_u32_e32 v147, s58, v17
	v_and_b32_e32 v0, 0x78, v0
	v_mov_b64_e32 v[36:37], s[14:15]
	v_mad_i64_i32 v[18:19], s[4:5], v147, s33, v[36:37]
	v_lshlrev_b32_e32 v0, 1, v0
	v_add_u32_e32 v22, 32, v147
	v_lshl_add_u64 v[18:19], v[18:19], 0, v[0:1]
	v_mad_i64_i32 v[22:23], s[4:5], v22, s33, v[36:37]
	v_add_co_u32_e32 v26, vcc, s3, v18
	s_min_i32 s4, s83, 1
	s_nop 0
	v_addc_co_u32_e32 v27, vcc, 0, v19, vcc
	v_lshl_add_u64 v[22:23], v[22:23], 0, v[0:1]
	v_lshl_add_u32 v40, s4, 6, v147
	v_add_co_u32_e32 v30, vcc, s3, v22
	v_mad_i64_i32 v[32:33], s[4:5], v40, s33, v[36:37]
	s_nop 0
	v_addc_co_u32_e32 v31, vcc, 0, v23, vcc
	v_lshl_add_u64 v[32:33], v[32:33], 0, v[0:1]
	v_add_u32_e32 v40, 32, v40
	v_add_co_u32_e32 v38, vcc, s3, v32
	v_mad_i64_i32 v[36:37], s[4:5], v40, s33, v[36:37]
	v_ashrrev_i32_e32 v15, 31, v14
	v_addc_co_u32_e32 v39, vcc, 0, v33, vcc
	v_lshl_add_u64 v[36:37], v[36:37], 0, v[0:1]
	global_load_dwordx4 v[2:5], v[34:35], off offset:3104
	global_load_dwordx4 v[6:9], v[34:35], off offset:3136
	global_load_dwordx4 v[10:13], v[34:35], off offset:3168
	global_load_dwordx4 v[96:99], v[34:35], off offset:3200
	global_load_dwordx4 v[100:103], v[34:35], off offset:3232
	global_load_dwordx4 v[104:107], v[34:35], off offset:3264
	v_lshlrev_b64 v[14:15], 9, v[14:15]
	global_load_dwordx4 v[108:111], v[34:35], off offset:3296
	global_load_dwordx4 v[18:21], v[26:27], off
	global_load_dwordx4 v[22:25], v[30:31], off
	s_nop 0
	global_load_dwordx4 v[26:29], v[26:27], off offset:256
	v_add_co_u32_e32 v36, vcc, 0x1000, v36
	v_lshl_add_u64 v[14:15], s[16:17], 0, v[14:15]
	global_load_dwordx4 v[30:33], v[30:31], off offset:256
	s_nop 0
	global_load_dwordx4 v[116:119], v[38:39], off
	v_addc_co_u32_e32 v37, vcc, 0, v37, vcc
	global_load_dwordx4 v[120:123], v[38:39], off offset:256
	global_load_dwordx4 v[128:131], v[36:37], off
	global_load_dwordx4 v[112:115], v[34:35], off offset:3072
	global_load_dwordx2 v[150:151], v[14:15], off
	global_load_dwordx4 v[124:127], v[36:37], off offset:256
	v_and_b32_e32 v16, 15, v16
	v_lshlrev_b32_e32 v34, 2, v16
	v_lshlrev_b32_e32 v35, 1, v17
	v_lshl_add_u32 v153, v16, 4, 0
	v_mul_u32_u24_e32 v155, 0x480, v16
	v_and_b32_e32 v16, 6, v35
	v_bfe_u32 v36, v17, 2, 1
	v_bfe_u32 v37, v17, 3, 1
	v_and_b32_e32 v38, -13, v17
	v_lshl_or_b32 v38, v36, 3, v38
	v_lshl_or_b32 v38, v37, 2, v38
	v_and_b32_e32 v34, 0x38, v34
	v_bitop3_b32 v36, v38, v34, -4 bitop3:0x6c
	v_mul_lo_u32 v154, v17, s97
	v_add_u32_e32 v162, 0, v16
	v_lshlrev_b32_e32 v163, 1, v36
	v_add_u32_e32 v35, v153, v154
	v_add3_u32 v16, v162, v163, v155
	s_mov_b64 s[4:5], -1
	s_cmp_gt_i32 s83, -1
	v_lshlrev_b32_e32 v152, 2, v81
	s_waitcnt vmcnt(9)
	ds_write_b128 v35, v[18:21]
	s_waitcnt vmcnt(7)
	ds_write_b16 v16, v26 offset:34816
	ds_write_b16_d16_hi v16, v26 offset:34960
	ds_write_b16 v16, v27 offset:35104
	ds_write_b16_d16_hi v16, v27 offset:35248
	ds_write_b16 v16, v28 offset:35392
	ds_write_b16_d16_hi v16, v28 offset:35536
	ds_write_b16 v16, v29 offset:35680
	ds_write_b16_d16_hi v16, v29 offset:35824
	v_add_u32_e32 v16, 32, v38
	v_bitop3_b32 v16, v16, v34, -4 bitop3:0x6c
	v_lshlrev_b32_e32 v164, 1, v16
	v_add3_u32 v16, v162, v164, v155
	ds_write_b128 v35, v[22:25] offset:8704
	s_waitcnt vmcnt(6)
	ds_write_b16 v16, v30 offset:34816
	ds_write_b16_d16_hi v16, v30 offset:34960
	ds_write_b16 v16, v31 offset:35104
	ds_write_b16_d16_hi v16, v31 offset:35248
	ds_write_b16 v16, v32 offset:35392
	ds_write_b16_d16_hi v16, v32 offset:35536
	ds_write_b16 v16, v33 offset:35680
	ds_write_b16_d16_hi v16, v33 offset:35824
	s_waitcnt lgkmcnt(0)
	s_barrier
	s_cbranch_scc0 .LBB0_591
	v_lshlrev_b32_e32 v146, 2, v81
	s_movk_i32 s4, 0x100
	v_lshlrev_b32_e64 v174, v146, s4
	s_movk_i32 s4, 0x200
	v_lshlrev_b32_e64 v175, v146, s4
	s_movk_i32 s4, 0x400
	v_lshlrev_b32_e64 v176, v146, s4
	s_movk_i32 s4, 0x800
	v_lshlrev_b32_e64 v177, v146, s4
	s_mov_b32 s4, 0x10000
	v_lshlrev_b32_e64 v178, v146, s4
	s_mov_b32 s4, 0x20000
	v_lshlrev_b32_e64 v179, v146, s4
	s_mov_b32 s4, 0x40000
	v_lshlrev_b32_e64 v180, v146, s4
	s_mov_b32 s4, 0x80000
	v_lshrrev_b32_e32 v16, 3, v80
	v_lshlrev_b32_e64 v181, v146, s4
	s_mov_b32 s4, 0x1000000
	v_xor_b32_e32 v16, v81, v16
	v_lshlrev_b32_e64 v192, v146, s4
	s_brev_b32 s4, 64
	v_lshlrev_b32_e32 v17, 2, v16
	v_lshrrev_b32_e32 v168, 4, v80
	v_xor_b32_e32 v168, v81, v168
	v_lshlrev_b32_e32 v168, 4, v168
	v_lshlrev_b32_e64 v193, v146, s4
	s_brev_b32 s4, 32
	v_add_u32_e32 v16, v145, v80
	v_mov_b32_e32 v30, v1
	v_mov_b32_e32 v31, v1
	v_xor_b32_e32 v165, 8, v17
	v_lshlrev_b32_e64 v194, v146, s4
	s_brev_b32 s4, 16
	v_sub_u32_e32 v196, v16, v146
	v_mov_b32_e32 v16, v1
	v_mov_b32_e32 v17, v1
	v_mov_b32_e32 v18, v1
	v_mov_b32_e32 v19, v1
	v_mov_b32_e32 v20, v1
	v_mov_b32_e32 v21, v1
	v_mov_b32_e32 v22, v1
	v_mov_b32_e32 v23, v1
	v_mov_b32_e32 v24, v1
	v_mov_b32_e32 v25, v1
	v_mov_b32_e32 v26, v1
	v_mov_b32_e32 v27, v1
	v_mov_b32_e32 v28, v1
	v_mov_b32_e32 v29, v1
	v_mov_b64_e32 v[46:47], v[30:31]
	v_mov_b64_e32 v[62:63], v[30:31]
	v_mov_b64_e32 v[78:79], v[30:31]
	s_mov_b32 s30, 2
	v_lshl_add_u32 v166, v81, 4, 0
	v_mad_u32_u24 v167, v80, s60, 0
	v_mul_u32_u24_e32 v169, 0x110, v80
	v_lshlrev_b32_e64 v170, v146, 1
	v_lshlrev_b32_e64 v171, v146, 2
	v_lshlrev_b32_e64 v172, v146, 4
	v_lshlrev_b32_e64 v173, v146, 8
	v_lshlrev_b32_e64 v195, v146, s4
	v_mov_b32_e32 v198, 0
	v_mov_b32_e32 v201, 0xff800000
	s_movk_i32 s31, 0xbf
	v_mov_b64_e32 v[44:45], v[28:29]
	v_mov_b64_e32 v[42:43], v[26:27]
	v_mov_b64_e32 v[40:41], v[24:25]
	v_mov_b64_e32 v[38:39], v[22:23]
	v_mov_b64_e32 v[36:37], v[20:21]
	v_mov_b64_e32 v[34:35], v[18:19]
	v_mov_b64_e32 v[32:33], v[16:17]
	v_mov_b64_e32 v[60:61], v[28:29]
	v_mov_b64_e32 v[58:59], v[26:27]
	v_mov_b64_e32 v[56:57], v[24:25]
	v_mov_b64_e32 v[54:55], v[22:23]
	v_mov_b64_e32 v[52:53], v[20:21]
	v_mov_b64_e32 v[50:51], v[18:19]
	v_mov_b64_e32 v[48:49], v[16:17]
	v_mov_b64_e32 v[76:77], v[28:29]
	v_mov_b64_e32 v[74:75], v[26:27]
	v_mov_b64_e32 v[72:73], v[24:25]
	v_mov_b64_e32 v[70:71], v[22:23]
	v_mov_b64_e32 v[68:69], v[20:21]
	v_mov_b64_e32 v[66:67], v[18:19]
	v_mov_b64_e32 v[64:65], v[16:17]

; #define LAS __attribute__((address_space(3)))
; __device__ __forceinline__ f32x16 mma32(const h16x8 a, const h16x8 b, const f32x16 c) { return __builtin_amdgcn_mfma_f32_32x32x16_f16(a, b, c, 0, 0, 0); }
; __device__ __forceinline__ void dsa_attn_item(CParams& p, LAS unsigned char* lds, int b, int qb, int tid_in, int wave) {
;     ...
;     for (int kt = 0; kt < nkt; ++kt) {
;         const int k0 = kt * 64; const int cur = kt & 1;
;         const LAS h16* Ks = Ks0 + cur * 8704; const LAS h16* Vt = Vt0 + cur * 9216;
;         const unsigned long long mk = mkn; mkn = bmq[kt + 1 < nkt ? kt + 1 : kt];
;         if (kt + 1 < nkt) ATT_STAGE(cur ^ 1, 2048, 2176, kt + 2);
;         if (__ballot(mk != 0ull) != 0ull) {
;             const bool far = (k0 + 63 + 128 <= q0);
;             const float bfar = bdh[128];
; #pragma unroll
;             for (int sub = 0; sub < 2; ++sub) {
;                 const unsigned mw = (unsigned)(mk >> (32 * sub));
;                 if (__ballot(mw != 0u) == 0ull) continue;
;                 f32x16 sc;
; #pragma unroll
;                 for (int i = 0; i < 16; ++i) sc[i] = 0.f;
; #pragma unroll
;                 for (int s = 0; s < 8; ++s) sc = mma32(*(const LAS h16x8*)(Ks + (32 * sub + r) * 136 + 16 * s + 8 * hh), qf[s], sc);
;                 float mx = -INFINITY;
; #pragma unroll
;                 for (int i = 0; i < 16; ++i) { const int ko = (i & 3) + 8 * (i >> 2) + 4 * hh; const int dist = qp - (k0 + 32 * sub + ko);
;                     float bias = bfar; if (!far) bias = bdh[dist < 0 ? 0 : (dist < 128 ? dist : 128)];
;                     const float v = ((mw >> ko) & 1u) ? sc[i] + bias : -INFINITY; sc[i] = v; mx = fmaxf(mx, v); }
.LBB0_514:
	s_waitcnt vmcnt(2)
	v_cmp_ne_u64_e32 vcc, 0, v[150:151]
	s_cbranch_vccz .LBB0_588
	s_and_b32 s4, s34, 1
	s_mul_i32 s5, s4, 0x4400
	s_mulk_i32 s4, 0x4800
	v_add3_u32 v197, v166, v169, s5
	v_add3_u32 v199, v167, v168, s4
	v_readfirstlane_b32 s6, v145
	v_cmp_ne_u32_e32 vcc, 0, v150
	s_cbranch_vccz .LdsaA_s0_skip
	ds_read_b128 v[80:83], v197 offset:0
	ds_read_b128 v[84:87], v197 offset:32
	ds_read_b128 v[88:91], v197 offset:64
	ds_read_b128 v[92:95], v197 offset:96
	ds_read_b128 v[202:205], v197 offset:128
	ds_read_b128 v[206:209], v197 offset:160
	ds_read_b128 v[210:213], v197 offset:192
	ds_read_b128 v[228:231], v197 offset:224
	ds_read_b32 v200, v184 offset:512
	s_waitcnt lgkmcnt(5)
	v_mfma_f32_32x32x16_f16 v[236:251], v[80:83], v[112:115], 0
	v_mfma_f32_32x32x16_f16 v[236:251], v[84:87], v[2:5], v[236:251]
	v_mfma_f32_32x32x16_f16 v[236:251], v[88:91], v[6:9], v[236:251]
	v_mfma_f32_32x32x16_f16 v[236:251], v[92:95], v[10:13], v[236:251]
	s_waitcnt lgkmcnt(1)
	v_mfma_f32_32x32x16_f16 v[236:251], v[202:205], v[96:99], v[236:251]
	v_mfma_f32_32x32x16_f16 v[236:251], v[206:209], v[100:103], v[236:251]
	v_mfma_f32_32x32x16_f16 v[236:251], v[210:213], v[104:107], v[236:251]
	v_mfma_f32_32x32x16_f16 v[236:251], v[228:231], v[108:111], v[236:251]
	v_lshrrev_b32_e32 v214, v146, v150
	s_cmp_le_i32 s31, s6
	s_cbranch_scc1 .LdsaA_s0_far
	v_subrev_u32_e32 v202, 0, v196
	v_med3_i32 v202, v202, 0, v226
	v_lshl_add_u32 v202, v202, 2, v184
	ds_read_b32 v202, v202
	v_subrev_u32_e32 v203, 1, v196
	v_med3_i32 v203, v203, 0, v226
	v_lshl_add_u32 v203, v203, 2, v184
	ds_read_b32 v203, v203
	v_subrev_u32_e32 v204, 2, v196
	v_med3_i32 v204, v204, 0, v226
	v_lshl_add_u32 v204, v204, 2, v184
	ds_read_b32 v204, v204
	v_subrev_u32_e32 v205, 3, v196
	v_med3_i32 v205, v205, 0, v226
	v_lshl_add_u32 v205, v205, 2, v184
	ds_read_b32 v205, v205
	v_subrev_u32_e32 v206, 8, v196
	v_med3_i32 v206, v206, 0, v226
	v_lshl_add_u32 v206, v206, 2, v184
	ds_read_b32 v206, v206
	v_subrev_u32_e32 v207, 9, v196
	v_med3_i32 v207, v207, 0, v226
	v_lshl_add_u32 v207, v207, 2, v184
	ds_read_b32 v207, v207
	v_subrev_u32_e32 v208, 10, v196
	v_med3_i32 v208, v208, 0, v226
	v_lshl_add_u32 v208, v208, 2, v184
	ds_read_b32 v208, v208
	v_subrev_u32_e32 v209, 11, v196
	v_med3_i32 v209, v209, 0, v226
	v_lshl_add_u32 v209, v209, 2, v184
	ds_read_b32 v209, v209
	v_subrev_u32_e32 v210, 16, v196
	v_med3_i32 v210, v210, 0, v226
	v_lshl_add_u32 v210, v210, 2, v184
	ds_read_b32 v210, v210
	v_subrev_u32_e32 v211, 17, v196
	v_med3_i32 v211, v211, 0, v226
	v_lshl_add_u32 v211, v211, 2, v184
	ds_read_b32 v211, v211
	v_subrev_u32_e32 v212, 18, v196
	v_med3_i32 v212, v212, 0, v226
	v_lshl_add_u32 v212, v212, 2, v184
	ds_read_b32 v212, v212
	v_subrev_u32_e32 v213, 19, v196
	v_med3_i32 v213, v213, 0, v226
	v_lshl_add_u32 v213, v213, 2, v184
	ds_read_b32 v213, v213
	v_subrev_u32_e32 v80, 24, v196
	v_med3_i32 v80, v80, 0, v226
	v_lshl_add_u32 v80, v80, 2, v184
	ds_read_b32 v80, v80
	v_subrev_u32_e32 v81, 25, v196
	v_med3_i32 v81, v81, 0, v226
	v_lshl_add_u32 v81, v81, 2, v184
	ds_read_b32 v81, v81
	v_subrev_u32_e32 v82, 26, v196
	v_med3_i32 v82, v82, 0, v226
	v_lshl_add_u32 v82, v82, 2, v184
	ds_read_b32 v82, v82
	v_subrev_u32_e32 v83, 27, v196
	v_med3_i32 v83, v83, 0, v226
	v_lshl_add_u32 v83, v83, 2, v184
	ds_read_b32 v83, v83
	s_waitcnt lgkmcnt(0)
	s_nop 2
	v_add_f32_e32 v236, v236, v202
	v_add_f32_e32 v237, v237, v203
	v_add_f32_e32 v238, v238, v204
	v_add_f32_e32 v239, v239, v205
	v_add_f32_e32 v240, v240, v206
	v_add_f32_e32 v241, v241, v207
	v_add_f32_e32 v242, v242, v208
	v_add_f32_e32 v243, v243, v209
	v_add_f32_e32 v244, v244, v210
	v_add_f32_e32 v245, v245, v211
	v_add_f32_e32 v246, v246, v212
	v_add_f32_e32 v247, v247, v213
	v_add_f32_e32 v248, v248, v80
	v_add_f32_e32 v249, v249, v81
	v_add_f32_e32 v250, v250, v82
	v_add_f32_e32 v251, v251, v83
	v_mov_b32_e32 v200, 0
	s_branch .LdsaA_s0_msk

; #define LAS __attribute__((address_space(3)))
; __device__ __forceinline__ f32x16 mma32(const h16x8 a, const h16x8 b, const f32x16 c) { return __builtin_amdgcn_mfma_f32_32x32x16_f16(a, b, c, 0, 0, 0); }
; __device__ __forceinline__ void dsa_attn_item(CParams& p, LAS unsigned char* lds, int b, int qb, int tid_in, int wave) {
;     ...
; #pragma unroll
;                 for (int i = 0; i < 16; ++i) { const int ko = (i & 3) + 8 * (i >> 2) + 4 * hh; const int dist = qp - (k0 + 32 * sub + ko);
;                     float bias = bfar; if (!far) bias = bdh[dist < 0 ? 0 : (dist < 128 ? dist : 128)];
;                     const float v = ((mw >> ko) & 1u) ? sc[i] + bias : -INFINITY; sc[i] = v; mx = fmaxf(mx, v); }
;                 mx = fmaxf(mx, __shfl_xor(mx, 32));
;                 const float m_new = fmaxf(m_run, mx);
;                 const float msafe = (m_new == -INFINITY) ? 0.f : m_new;
;                 const float alpha = __builtin_amdgcn_exp2f(m_run - msafe);
;                 const bool resc = __ballot(m_new > m_run) != 0ull;
;                 float ls = 0.f;
; #pragma unroll
;                 for (int i = 0; i < 16; ++i) { const float e = __builtin_amdgcn_exp2f(sc[i] - msafe); sc[i] = e; ls += e; }
;                 ls += __shfl_xor(ls, 32);
;                 l_run = l_run * alpha + ls; m_run = m_new;
;                 if (resc) {
; #pragma unroll
;                     for (int d = 0; d < 4; ++d)
; #pragma unroll
;                         for (int i = 0; i < 16; ++i) o[d][i] *= alpha;
;                 }
; #pragma unroll
;                 for (int s2 = 0; s2 < 2; ++s2) {
;                     h16x8 pf;
; #pragma unroll
;                     for (int jj = 0; jj < 8; ++jj) pf[jj] = (h16)sc[8 * s2 + jj];
; #pragma unroll
;                     for (int d = 0; d < 4; ++d) {
;                         const int coff = 32 * d * 72 + ((((sub << 1) | s2) ^ d) << 4);
;                         const h16x4 lo = *(const LAS h16x4*)(Vt + vlo + coff), hi = *(const LAS h16x4*)(Vt + vhi + coff);
;                         h16x8 vf; vf[0] = lo[0]; vf[1] = lo[1]; vf[2] = lo[2]; vf[3] = lo[3]; vf[4] = hi[0]; vf[5] = hi[1]; vf[6] = hi[2]; vf[7] = hi[3];
;                         o[d] = mma32(vf, pf, o[d]);
;                     }
;                 }
.LdsaA_s0_msk:
	v_bfe_i32 v80, v214, 0, 1
	v_bfi_b32 v236, v80, v236, v225
	v_bfe_i32 v81, v214, 1, 1
	v_bfi_b32 v237, v81, v237, v225
	v_bfe_i32 v82, v214, 2, 1
	v_bfi_b32 v238, v82, v238, v225
	v_bfe_i32 v83, v214, 3, 1
	v_bfi_b32 v239, v83, v239, v225
	v_bfe_i32 v80, v214, 8, 1
	v_bfi_b32 v240, v80, v240, v225
	v_bfe_i32 v81, v214, 9, 1
	v_bfi_b32 v241, v81, v241, v225
	v_bfe_i32 v82, v214, 10, 1
	v_bfi_b32 v242, v82, v242, v225
	v_bfe_i32 v83, v214, 11, 1
	v_bfi_b32 v243, v83, v243, v225
	v_bfe_i32 v80, v214, 16, 1
	v_bfi_b32 v244, v80, v244, v225
	v_bfe_i32 v81, v214, 17, 1
	v_bfi_b32 v245, v81, v245, v225
	v_bfe_i32 v82, v214, 18, 1
	v_bfi_b32 v246, v82, v246, v225
	v_bfe_i32 v83, v214, 19, 1
	v_bfi_b32 v247, v83, v247, v225
	v_bfe_i32 v80, v214, 24, 1
	v_bfi_b32 v248, v80, v248, v225
	v_bfe_i32 v81, v214, 25, 1
	v_bfi_b32 v249, v81, v249, v225
	v_bfe_i32 v82, v214, 26, 1
	v_bfi_b32 v250, v82, v250, v225
	v_bfe_i32 v83, v214, 27, 1
	v_bfi_b32 v251, v83, v251, v225
	v_max3_f32 v84, v236, v237, v238
	v_max3_f32 v84, v84, v239, v240
	v_max3_f32 v84, v84, v241, v242
	v_max3_f32 v84, v84, v243, v244
	v_max3_f32 v84, v84, v245, v246
	v_max3_f32 v84, v84, v247, v248
	v_max3_f32 v84, v84, v249, v250
	v_max_f32_e32 v84, v84, v251
	s_waitcnt lgkmcnt(0)
	v_add_f32_e32 v84, v84, v200
	ds_bpermute_b32 v215, v185, v84
	s_waitcnt lgkmcnt(0)
	v_max3_f32 v85, v201, v84, v215
	v_cmp_neq_f32_e32 vcc, s78, v85
	s_nop 1
	v_cndmask_b32_e32 v86, 0, v85, vcc
	v_sub_f32_e32 v88, v201, v86
	v_exp_f32_e32 v88, v88
	v_cmp_gt_f32_e32 vcc, v85, v201
	v_sub_f32_e32 v90, v86, v200
	v_mov_b32_e32 v201, v85
	v_pk_add_f32 v[236:237], v[236:237], v[90:91] op_sel_hi:[1,0] neg_lo:[0,1] neg_hi:[0,1]
	v_pk_add_f32 v[238:239], v[238:239], v[90:91] op_sel_hi:[1,0] neg_lo:[0,1] neg_hi:[0,1]
	v_pk_add_f32 v[240:241], v[240:241], v[90:91] op_sel_hi:[1,0] neg_lo:[0,1] neg_hi:[0,1]
	v_pk_add_f32 v[242:243], v[242:243], v[90:91] op_sel_hi:[1,0] neg_lo:[0,1] neg_hi:[0,1]
	v_pk_add_f32 v[244:245], v[244:245], v[90:91] op_sel_hi:[1,0] neg_lo:[0,1] neg_hi:[0,1]
	v_pk_add_f32 v[246:247], v[246:247], v[90:91] op_sel_hi:[1,0] neg_lo:[0,1] neg_hi:[0,1]
	v_pk_add_f32 v[248:249], v[248:249], v[90:91] op_sel_hi:[1,0] neg_lo:[0,1] neg_hi:[0,1]
	v_pk_add_f32 v[250:251], v[250:251], v[90:91] op_sel_hi:[1,0] neg_lo:[0,1] neg_hi:[0,1]
	v_exp_f32_e32 v236, v236
	v_exp_f32_e32 v237, v237
	v_exp_f32_e32 v238, v238
	v_exp_f32_e32 v239, v239
	v_exp_f32_e32 v240, v240
	v_exp_f32_e32 v241, v241
	v_exp_f32_e32 v242, v242
	v_exp_f32_e32 v243, v243
	v_exp_f32_e32 v244, v244
	v_exp_f32_e32 v245, v245
	v_exp_f32_e32 v246, v246
	v_exp_f32_e32 v247, v247
	v_exp_f32_e32 v248, v248
	v_exp_f32_e32 v249, v249
	v_exp_f32_e32 v250, v250
	v_exp_f32_e32 v251, v251
	v_pk_add_f32 v[92:93], v[236:237], v[238:239]
	v_pk_add_f32 v[92:93], v[92:93], v[240:241]
	v_pk_add_f32 v[92:93], v[92:93], v[242:243]
	v_pk_add_f32 v[92:93], v[92:93], v[244:245]
	v_pk_add_f32 v[92:93], v[92:93], v[246:247]
	v_pk_add_f32 v[92:93], v[92:93], v[248:249]
	v_pk_add_f32 v[92:93], v[92:93], v[250:251]
	s_nop 0
	v_add_f32_e32 v92, v92, v93
	ds_bpermute_b32 v215, v185, v92
	v_cvt_pk_f16_f32 v232, v236, v237
	v_cvt_pk_f16_f32 v233, v238, v239
	v_cvt_pk_f16_f32 v234, v240, v241
	v_cvt_pk_f16_f32 v235, v242, v243
	v_cvt_pk_f16_f32 v228, v244, v245
	v_cvt_pk_f16_f32 v229, v246, v247
	v_cvt_pk_f16_f32 v230, v248, v249
	v_cvt_pk_f16_f32 v231, v250, v251
	s_waitcnt lgkmcnt(0)
	v_add_f32_e32 v92, v92, v215
	v_fma_f32 v198, v198, v88, v92
	ds_read_b128 v[236:239], v199 offset:34848
	ds_read_b128 v[240:243], v199 offset:39424
	ds_read_b128 v[244:247], v199 offset:44128
	ds_read_b128 v[248:251], v199 offset:48704
	s_cbranch_vccz .LdsaA_s0_noresc
	v_pk_mul_f32 v[64:65], v[64:65], v[88:89] op_sel_hi:[1,0]
	v_pk_mul_f32 v[66:67], v[66:67], v[88:89] op_sel_hi:[1,0]
	v_pk_mul_f32 v[68:69], v[68:69], v[88:89] op_sel_hi:[1,0]
	v_pk_mul_f32 v[70:71], v[70:71], v[88:89] op_sel_hi:[1,0]
	v_pk_mul_f32 v[72:73], v[72:73], v[88:89] op_sel_hi:[1,0]
	v_pk_mul_f32 v[74:75], v[74:75], v[88:89] op_sel_hi:[1,0]
	v_pk_mul_f32 v[76:77], v[76:77], v[88:89] op_sel_hi:[1,0]
	v_pk_mul_f32 v[78:79], v[78:79], v[88:89] op_sel_hi:[1,0]
	v_pk_mul_f32 v[48:49], v[48:49], v[88:89] op_sel_hi:[1,0]
	v_pk_mul_f32 v[50:51], v[50:51], v[88:89] op_sel_hi:[1,0]
	v_pk_mul_f32 v[52:53], v[52:53], v[88:89] op_sel_hi:[1,0]
	v_pk_mul_f32 v[54:55], v[54:55], v[88:89] op_sel_hi:[1,0]
	v_pk_mul_f32 v[56:57], v[56:57], v[88:89] op_sel_hi:[1,0]
	v_pk_mul_f32 v[58:59], v[58:59], v[88:89] op_sel_hi:[1,0]
	v_pk_mul_f32 v[60:61], v[60:61], v[88:89] op_sel_hi:[1,0]
	v_pk_mul_f32 v[62:63], v[62:63], v[88:89] op_sel_hi:[1,0]
	v_pk_mul_f32 v[32:33], v[32:33], v[88:89] op_sel_hi:[1,0]
	v_pk_mul_f32 v[34:35], v[34:35], v[88:89] op_sel_hi:[1,0]
	v_pk_mul_f32 v[36:37], v[36:37], v[88:89] op_sel_hi:[1,0]
	v_pk_mul_f32 v[38:39], v[38:39], v[88:89] op_sel_hi:[1,0]
	v_pk_mul_f32 v[40:41], v[40:41], v[88:89] op_sel_hi:[1,0]
	v_pk_mul_f32 v[42:43], v[42:43], v[88:89] op_sel_hi:[1,0]
	v_pk_mul_f32 v[44:45], v[44:45], v[88:89] op_sel_hi:[1,0]
	v_pk_mul_f32 v[46:47], v[46:47], v[88:89] op_sel_hi:[1,0]
	v_pk_mul_f32 v[16:17], v[16:17], v[88:89] op_sel_hi:[1,0]
	v_pk_mul_f32 v[18:19], v[18:19], v[88:89] op_sel_hi:[1,0]
	v_pk_mul_f32 v[20:21], v[20:21], v[88:89] op_sel_hi:[1,0]
	v_pk_mul_f32 v[22:23], v[22:23], v[88:89] op_sel_hi:[1,0]
	v_pk_mul_f32 v[24:25], v[24:25], v[88:89] op_sel_hi:[1,0]
	v_pk_mul_f32 v[26:27], v[26:27], v[88:89] op_sel_hi:[1,0]
	v_pk_mul_f32 v[28:29], v[28:29], v[88:89] op_sel_hi:[1,0]
	v_pk_mul_f32 v[30:31], v[30:31], v[88:89] op_sel_hi:[1,0]
.LdsaA_s0_noresc:
	ds_read_b128 v[80:83], v199 offset:34816
	ds_read_b128 v[84:87], v199 offset:39456
	ds_read_b128 v[88:91], v199 offset:44096
	ds_read_b128 v[92:95], v199 offset:48736
	s_waitcnt lgkmcnt(4)
	v_mfma_f32_32x32x16_f16 v[64:79], v[236:239], v[228:231], v[64:79]
	v_mfma_f32_32x32x16_f16 v[48:63], v[240:243], v[228:231], v[48:63]
	v_mfma_f32_32x32x16_f16 v[32:47], v[244:247], v[228:231], v[32:47]
	v_mfma_f32_32x32x16_f16 v[16:31], v[248:251], v[228:231], v[16:31]
	s_waitcnt lgkmcnt(0)
	v_mfma_f32_32x32x16_f16 v[64:79], v[80:83], v[232:235], v[64:79]
	v_mfma_f32_32x32x16_f16 v[48:63], v[84:87], v[232:235], v[48:63]
	v_mfma_f32_32x32x16_f16 v[32:47], v[88:91], v[232:235], v[32:47]
	v_mfma_f32_32x32x16_f16 v[16:31], v[92:95], v[232:235], v[16:31]

; #define LAS __attribute__((address_space(3)))
; __device__ __forceinline__ f32x16 mma32(const h16x8 a, const h16x8 b, const f32x16 c) { return __builtin_amdgcn_mfma_f32_32x32x16_f16(a, b, c, 0, 0, 0); }
; __device__ __forceinline__ void dsa_attn_item(CParams& p, LAS unsigned char* lds, int b, int qb, int tid_in, int wave) {
;     ...
; #pragma unroll
;                 for (int i = 0; i < 16; ++i) { const int ko = (i & 3) + 8 * (i >> 2) + 4 * hh; const int dist = qp - (k0 + 32 * sub + ko);
;                     float bias = bfar; if (!far) bias = bdh[dist < 0 ? 0 : (dist < 128 ? dist : 128)];
;                     const float v = ((mw >> ko) & 1u) ? sc[i] + bias : -INFINITY; sc[i] = v; mx = fmaxf(mx, v); }
;                 mx = fmaxf(mx, __shfl_xor(mx, 32));
;                 const float m_new = fmaxf(m_run, mx);
;                 const float msafe = (m_new == -INFINITY) ? 0.f : m_new;
;                 const float alpha = __builtin_amdgcn_exp2f(m_run - msafe);
;                 const bool resc = __ballot(m_new > m_run) != 0ull;
;                 float ls = 0.f;
; #pragma unroll
;                 for (int i = 0; i < 16; ++i) { const float e = __builtin_amdgcn_exp2f(sc[i] - msafe); sc[i] = e; ls += e; }
;                 ls += __shfl_xor(ls, 32);
;                 l_run = l_run * alpha + ls; m_run = m_new;
;                 if (resc) {
; #pragma unroll
;                     for (int d = 0; d < 4; ++d)
; #pragma unroll
;                         for (int i = 0; i < 16; ++i) o[d][i] *= alpha;
;                 }
; #pragma unroll
;                 for (int s2 = 0; s2 < 2; ++s2) {
;                     h16x8 pf;
; #pragma unroll
;                     for (int jj = 0; jj < 8; ++jj) pf[jj] = (h16)sc[8 * s2 + jj];
; #pragma unroll
;                     for (int d = 0; d < 4; ++d) {
;                         const int coff = 32 * d * 72 + ((((sub << 1) | s2) ^ d) << 4);
;                         const h16x4 lo = *(const LAS h16x4*)(Vt + vlo + coff), hi = *(const LAS h16x4*)(Vt + vhi + coff);
;                         h16x8 vf; vf[0] = lo[0]; vf[1] = lo[1]; vf[2] = lo[2]; vf[3] = lo[3]; vf[4] = hi[0]; vf[5] = hi[1]; vf[6] = hi[2]; vf[7] = hi[3];
;                         o[d] = mma32(vf, pf, o[d]);
;                     }
;                 }
.LdsaA_s1_msk:
	v_bfe_i32 v80, v214, 0, 1
	v_bfi_b32 v236, v80, v236, v225
	v_bfe_i32 v81, v214, 1, 1
	v_bfi_b32 v237, v81, v237, v225
	v_bfe_i32 v82, v214, 2, 1
	v_bfi_b32 v238, v82, v238, v225
	v_bfe_i32 v83, v214, 3, 1
	v_bfi_b32 v239, v83, v239, v225
	v_bfe_i32 v80, v214, 8, 1
	v_bfi_b32 v240, v80, v240, v225
	v_bfe_i32 v81, v214, 9, 1
	v_bfi_b32 v241, v81, v241, v225
	v_bfe_i32 v82, v214, 10, 1
	v_bfi_b32 v242, v82, v242, v225
	v_bfe_i32 v83, v214, 11, 1
	v_bfi_b32 v243, v83, v243, v225
	v_bfe_i32 v80, v214, 16, 1
	v_bfi_b32 v244, v80, v244, v225
	v_bfe_i32 v81, v214, 17, 1
	v_bfi_b32 v245, v81, v245, v225
	v_bfe_i32 v82, v214, 18, 1
	v_bfi_b32 v246, v82, v246, v225
	v_bfe_i32 v83, v214, 19, 1
	v_bfi_b32 v247, v83, v247, v225
	v_bfe_i32 v80, v214, 24, 1
	v_bfi_b32 v248, v80, v248, v225
	v_bfe_i32 v81, v214, 25, 1
	v_bfi_b32 v249, v81, v249, v225
	v_bfe_i32 v82, v214, 26, 1
	v_bfi_b32 v250, v82, v250, v225
	v_bfe_i32 v83, v214, 27, 1
	v_bfi_b32 v251, v83, v251, v225
	v_max3_f32 v84, v236, v237, v238
	v_max3_f32 v84, v84, v239, v240
	v_max3_f32 v84, v84, v241, v242
	v_max3_f32 v84, v84, v243, v244
	v_max3_f32 v84, v84, v245, v246
	v_max3_f32 v84, v84, v247, v248
	v_max3_f32 v84, v84, v249, v250
	v_max_f32_e32 v84, v84, v251
	s_waitcnt lgkmcnt(0)
	v_add_f32_e32 v84, v84, v200
	ds_bpermute_b32 v215, v185, v84
	s_waitcnt lgkmcnt(0)
	v_max3_f32 v85, v201, v84, v215
	v_cmp_neq_f32_e32 vcc, s78, v85
	s_nop 1
	v_cndmask_b32_e32 v86, 0, v85, vcc
	v_sub_f32_e32 v88, v201, v86
	v_exp_f32_e32 v88, v88
	v_cmp_gt_f32_e32 vcc, v85, v201
	v_sub_f32_e32 v90, v86, v200
	v_mov_b32_e32 v201, v85
	v_pk_add_f32 v[236:237], v[236:237], v[90:91] op_sel_hi:[1,0] neg_lo:[0,1] neg_hi:[0,1]
	v_pk_add_f32 v[238:239], v[238:239], v[90:91] op_sel_hi:[1,0] neg_lo:[0,1] neg_hi:[0,1]
	v_pk_add_f32 v[240:241], v[240:241], v[90:91] op_sel_hi:[1,0] neg_lo:[0,1] neg_hi:[0,1]
	v_pk_add_f32 v[242:243], v[242:243], v[90:91] op_sel_hi:[1,0] neg_lo:[0,1] neg_hi:[0,1]
	v_pk_add_f32 v[244:245], v[244:245], v[90:91] op_sel_hi:[1,0] neg_lo:[0,1] neg_hi:[0,1]
	v_pk_add_f32 v[246:247], v[246:247], v[90:91] op_sel_hi:[1,0] neg_lo:[0,1] neg_hi:[0,1]
	v_pk_add_f32 v[248:249], v[248:249], v[90:91] op_sel_hi:[1,0] neg_lo:[0,1] neg_hi:[0,1]
	v_pk_add_f32 v[250:251], v[250:251], v[90:91] op_sel_hi:[1,0] neg_lo:[0,1] neg_hi:[0,1]
	v_exp_f32_e32 v236, v236
	v_exp_f32_e32 v237, v237
	v_exp_f32_e32 v238, v238
	v_exp_f32_e32 v239, v239
	v_exp_f32_e32 v240, v240
	v_exp_f32_e32 v241, v241
	v_exp_f32_e32 v242, v242
	v_exp_f32_e32 v243, v243
	v_exp_f32_e32 v244, v244
	v_exp_f32_e32 v245, v245
	v_exp_f32_e32 v246, v246
	v_exp_f32_e32 v247, v247
	v_exp_f32_e32 v248, v248
	v_exp_f32_e32 v249, v249
	v_exp_f32_e32 v250, v250
	v_exp_f32_e32 v251, v251
	v_pk_add_f32 v[92:93], v[236:237], v[238:239]
	v_pk_add_f32 v[92:93], v[92:93], v[240:241]
	v_pk_add_f32 v[92:93], v[92:93], v[242:243]
	v_pk_add_f32 v[92:93], v[92:93], v[244:245]
	v_pk_add_f32 v[92:93], v[92:93], v[246:247]
	v_pk_add_f32 v[92:93], v[92:93], v[248:249]
	v_pk_add_f32 v[92:93], v[92:93], v[250:251]
	s_nop 0
	v_add_f32_e32 v92, v92, v93
	ds_bpermute_b32 v215, v185, v92
	v_cvt_pk_f16_f32 v232, v236, v237
	v_cvt_pk_f16_f32 v233, v238, v239
	v_cvt_pk_f16_f32 v234, v240, v241
	v_cvt_pk_f16_f32 v235, v242, v243
	v_cvt_pk_f16_f32 v228, v244, v245
	v_cvt_pk_f16_f32 v229, v246, v247
	v_cvt_pk_f16_f32 v230, v248, v249
	v_cvt_pk_f16_f32 v231, v250, v251
	s_waitcnt lgkmcnt(0)
	v_add_f32_e32 v92, v92, v215
	v_fma_f32 v198, v198, v88, v92
	ds_read_b128 v[236:239], v199 offset:34912
	ds_read_b128 v[240:243], v199 offset:39488
	ds_read_b128 v[244:247], v199 offset:44064
	ds_read_b128 v[248:251], v199 offset:48640
	s_cbranch_vccz .LdsaA_s1_noresc
	v_pk_mul_f32 v[64:65], v[64:65], v[88:89] op_sel_hi:[1,0]
	v_pk_mul_f32 v[66:67], v[66:67], v[88:89] op_sel_hi:[1,0]
	v_pk_mul_f32 v[68:69], v[68:69], v[88:89] op_sel_hi:[1,0]
	v_pk_mul_f32 v[70:71], v[70:71], v[88:89] op_sel_hi:[1,0]
	v_pk_mul_f32 v[72:73], v[72:73], v[88:89] op_sel_hi:[1,0]
	v_pk_mul_f32 v[74:75], v[74:75], v[88:89] op_sel_hi:[1,0]
	v_pk_mul_f32 v[76:77], v[76:77], v[88:89] op_sel_hi:[1,0]
	v_pk_mul_f32 v[78:79], v[78:79], v[88:89] op_sel_hi:[1,0]
	v_pk_mul_f32 v[48:49], v[48:49], v[88:89] op_sel_hi:[1,0]
	v_pk_mul_f32 v[50:51], v[50:51], v[88:89] op_sel_hi:[1,0]
	v_pk_mul_f32 v[52:53], v[52:53], v[88:89] op_sel_hi:[1,0]
	v_pk_mul_f32 v[54:55], v[54:55], v[88:89] op_sel_hi:[1,0]
	v_pk_mul_f32 v[56:57], v[56:57], v[88:89] op_sel_hi:[1,0]
	v_pk_mul_f32 v[58:59], v[58:59], v[88:89] op_sel_hi:[1,0]
	v_pk_mul_f32 v[60:61], v[60:61], v[88:89] op_sel_hi:[1,0]
	v_pk_mul_f32 v[62:63], v[62:63], v[88:89] op_sel_hi:[1,0]
	v_pk_mul_f32 v[32:33], v[32:33], v[88:89] op_sel_hi:[1,0]
	v_pk_mul_f32 v[34:35], v[34:35], v[88:89] op_sel_hi:[1,0]
	v_pk_mul_f32 v[36:37], v[36:37], v[88:89] op_sel_hi:[1,0]
	v_pk_mul_f32 v[38:39], v[38:39], v[88:89] op_sel_hi:[1,0]
	v_pk_mul_f32 v[40:41], v[40:41], v[88:89] op_sel_hi:[1,0]
	v_pk_mul_f32 v[42:43], v[42:43], v[88:89] op_sel_hi:[1,0]
	v_pk_mul_f32 v[44:45], v[44:45], v[88:89] op_sel_hi:[1,0]
	v_pk_mul_f32 v[46:47], v[46:47], v[88:89] op_sel_hi:[1,0]
	v_pk_mul_f32 v[16:17], v[16:17], v[88:89] op_sel_hi:[1,0]
	v_pk_mul_f32 v[18:19], v[18:19], v[88:89] op_sel_hi:[1,0]
	v_pk_mul_f32 v[20:21], v[20:21], v[88:89] op_sel_hi:[1,0]
	v_pk_mul_f32 v[22:23], v[22:23], v[88:89] op_sel_hi:[1,0]
	v_pk_mul_f32 v[24:25], v[24:25], v[88:89] op_sel_hi:[1,0]
	v_pk_mul_f32 v[26:27], v[26:27], v[88:89] op_sel_hi:[1,0]
	v_pk_mul_f32 v[28:29], v[28:29], v[88:89] op_sel_hi:[1,0]
	v_pk_mul_f32 v[30:31], v[30:31], v[88:89] op_sel_hi:[1,0]
.LdsaA_s1_noresc:
	ds_read_b128 v[80:83], v199 offset:34880
	ds_read_b128 v[84:87], v199 offset:39520
	ds_read_b128 v[88:91], v199 offset:44032
	ds_read_b128 v[92:95], v199 offset:48672
	s_waitcnt lgkmcnt(4)
	v_mfma_f32_32x32x16_f16 v[64:79], v[236:239], v[228:231], v[64:79]
	v_mfma_f32_32x32x16_f16 v[48:63], v[240:243], v[228:231], v[48:63]
	v_mfma_f32_32x32x16_f16 v[32:47], v[244:247], v[228:231], v[32:47]
	v_mfma_f32_32x32x16_f16 v[16:31], v[248:251], v[228:231], v[16:31]
	s_waitcnt lgkmcnt(0)
	v_mfma_f32_32x32x16_f16 v[64:79], v[80:83], v[232:235], v[64:79]
	v_mfma_f32_32x32x16_f16 v[48:63], v[84:87], v[232:235], v[48:63]
	v_mfma_f32_32x32x16_f16 v[32:47], v[88:91], v[232:235], v[32:47]
	v_mfma_f32_32x32x16_f16 v[16:31], v[92:95], v[232:235], v[16:31]

; __device__ __forceinline__ void diff_attn_item(CParams& p, int j, int layer, LAS unsigned char* lds, int b, int h, int qb, int tid_in, int lane_in, int wave) {
;     ...
;     const int mp = wave >> 2, qs = wave & 3, r = lane & 31, hh = lane >> 5;
;     const int tb0 = b * SEQ; const int q0 = qb * 128 + 32 * qs;
;     if (tid < 129) bdl[tid] = bd[tid];
;     h16x8 qf[4];
; #pragma unroll
;     for (int s = 0; s < 4; ++s) qf[s] = *(const h16x8*)(proj + (size_t)(tb0 + q0 + r) * OD_N + h * 128 + mp * 64 + 16 * s + 8 * hh);
;     f32x16 o[4];
; #pragma unroll
;     for (int d = 0; d < 4; ++d)
; #pragma unroll
;         for (int i = 0; i < 16; ++i) o[d][i] = 0.f;
;     float m_run = -INFINITY, l_run = 0.f;
;     const int qp = q0 + r;
;     const int vlo = r * 72 + ((hh ^ (r >> 3)) << 2), vhi = r * 72 + (((hh ^ (r >> 3)) ^ 2) << 2);
;     const int nkt = 2 * (qb + 1);
;     h16x8 pk[2], pv[2];
; #pragma unroll
;     for (int i = 0; i < 2; ++i) { const int key = i * 32 + (tid >> 4), ch = tid & 15;
;         pk[i] = *(const h16x8*)(proj + (size_t)(tb0 + key) * OD_N + 512 + h * 128 + ch * 8);
;         pv[i] = *(const h16x8*)(proj + (size_t)(tb0 + key) * OD_N + 1024 + h * 128 + ch * 8); }
;     ...
;     ATT_STAGE(0, 512 + h * 128, 1024 + h * 128, 1);
;     __syncthreads();
.LBB0_597:
	s_or_b64 exec, exec, s[4:5]
	s_lshl_b32 s4, s35, 2
	s_and_b32 s4, s4, 24
	s_add_i32 s4, s4, s73
	s_and_b32 s4, s4, 31
	s_and_b32 s5, s35, 1
	s_xor_b32 s6, s4, 31
	s_cmp_eq_u32 s5, 0
	s_cselect_b32 s6, s4, s6
	s_lshl_b32 s4, s35, 10
	s_and_b32 s4, s4, 0x1000
	s_or_b32 s7, s4, s34
	v_ashrrev_i32_e32 v3, 4, v2
	v_add_u32_e32 v200, s7, v3
	v_lshlrev_b32_e32 v0, 4, v2
	s_lshl_b32 s30, s6, 7
	v_mov_b64_e32 v[20:21], s[14:15]
	v_and_b32_e32 v22, 0xf0, v0
	v_add_u32_e32 v0, 32, v200
	v_and_b32_e32 v198, 31, v2
	v_or_b32_e32 v199, s30, v186
	s_lshl_b32 s58, s12, 8
	v_mad_i64_i32 v[4:5], s[4:5], v200, s33, v[20:21]
	v_mad_i64_i32 v[12:13], s[4:5], v0, s33, v[20:21]
	s_lshl_b32 s36, s12, 7
	s_lshl_b32 s37, s6, 1
	v_or3_b32 v0, s7, v198, v199
	s_add_u32 s4, s14, s58
	v_mad_u64_u32 v[20:21], s[12:13], v0, s33, v[20:21]
	v_bfe_u32 v30, v2, 5, 1
	s_addc_u32 s5, s15, 0
	v_lshl_add_u64 v[20:21], v[20:21], 0, s[58:59]
	v_lshl_add_u64 v[4:5], v[4:5], 0, s[58:59]
	v_mov_b32_e32 v23, v1
	v_lshl_add_u64 v[12:13], v[12:13], 0, s[58:59]
	v_mov_b32_e32 v25, v1
	v_lshlrev_b32_e32 v24, 4, v30
	v_add_u32_e32 v28, 64, v200
	v_add_u32_e32 v31, 0x60, v200
	v_mov_b64_e32 v[26:27], s[4:5]
	v_lshl_add_u64 v[20:21], v[140:141], 1, v[20:21]
	v_lshl_add_u64 v[8:9], v[4:5], 0, v[22:23]
	v_lshl_add_u64 v[16:17], v[12:13], 0, v[22:23]
	v_mad_i64_i32 v[28:29], s[12:13], v28, s33, v[26:27]
	v_mad_i64_i32 v[26:27], s[12:13], v31, s33, v[26:27]
	v_lshl_add_u64 v[20:21], v[20:21], 0, v[24:25]
	global_load_dwordx4 v[4:7], v[8:9], off offset:1024
	s_nop 0
	global_load_dwordx4 v[8:11], v[8:9], off offset:2048
	s_nop 0
	global_load_dwordx4 v[12:15], v[16:17], off offset:1024
	s_nop 0
	global_load_dwordx4 v[16:19], v[16:17], off offset:2048
	v_lshl_add_u64 v[28:29], v[28:29], 0, v[22:23]
	v_lshl_add_u64 v[26:27], v[26:27], 0, v[22:23]
	global_load_dwordx4 v[110:113], v[20:21], off
	global_load_dwordx4 v[106:109], v[20:21], off offset:32
	global_load_dwordx4 v[102:105], v[20:21], off offset:64
	global_load_dwordx4 v[98:101], v[20:21], off offset:96
	global_load_dwordx4 v[126:129], v[28:29], off offset:1024
	global_load_dwordx4 v[118:121], v[28:29], off offset:2048
	global_load_dwordx4 v[122:125], v[26:27], off offset:1024
	global_load_dwordx4 v[114:117], v[26:27], off offset:2048
	v_and_b32_e32 v193, 63, v2
	v_bfe_u32 v20, v2, 3, 2
	v_and_b32_e32 v2, 15, v2
	v_lshlrev_b32_e32 v21, 2, v2
	v_lshlrev_b32_e32 v25, 1, v3
	v_lshl_add_u32 v202, v2, 4, 0
	v_mul_lo_u32 v203, v3, s97
	v_mul_u32_u24_e32 v204, 0x480, v2
	v_and_b32_e32 v25, 6, v25
	v_bfe_u32 v26, v3, 2, 1
	v_bfe_u32 v27, v3, 3, 1
	v_and_b32_e32 v2, -13, v3
	v_lshl_or_b32 v2, v26, 3, v2
	v_lshl_or_b32 v26, v27, 2, v2
	v_and_b32_e32 v21, 0x38, v21
	v_add_u32_e32 v2, 32, v26
	v_bitop3_b32 v3, v26, v21, -4 bitop3:0x6c
	v_bitop3_b32 v2, v2, v21, -4 bitop3:0x6c
	v_add_u32_e32 v205, 0, v25
	v_lshlrev_b32_e32 v206, 1, v3
	v_add_u32_e32 v27, v202, v203
	v_lshlrev_b32_e32 v207, 1, v2
	v_add3_u32 v2, v205, v206, v204
	v_xor_b32_e32 v20, v30, v20
	v_lshlrev_b32_e32 v26, 2, v20
	v_lshlrev_b32_e32 v192, 2, v30
	v_xor_b32_e32 v194, 8, v26
	v_add_u32_e32 v208, v187, v24
	v_bfe_u32 v196, v193, 4, 1
	v_xor_b32_e32 v196, v30, v196
	v_lshlrev_b32_e32 v196, 4, v196
	s_waitcnt vmcnt(29)
	v_lshl_add_u64 v[130:131], s[4:5], 0, v[22:23]
	v_mov_b32_e32 v3, v1
	s_mov_b32 s38, 0
	s_or_b32 s39, s37, 1
	v_or_b32_e32 v210, 31, v199
	v_mad_u32_u24 v195, v198, s60, 0
	v_mul_u32_u24_e32 v209, 0x110, v198
	v_mad_u32_u24 v211, v198, s97, v208
	v_mov_b32_e32 v197, 0
	v_mov_b32_e32 v201, 0xff800000
	s_movk_i32 s40, 0xbf
	s_waitcnt vmcnt(11)
	ds_write_b128 v27, v[4:7]
	s_waitcnt vmcnt(10)
	ds_write_b16 v2, v8 offset:34816
	ds_write_b16_d16_hi v2, v8 offset:34960
	ds_write_b16 v2, v9 offset:35104
	ds_write_b16_d16_hi v2, v9 offset:35248
	ds_write_b16 v2, v10 offset:35392
	ds_write_b16_d16_hi v2, v10 offset:35536
	ds_write_b16 v2, v11 offset:35680
	ds_write_b16_d16_hi v2, v11 offset:35824
	s_waitcnt vmcnt(9)
	ds_write_b128 v27, v[12:15] offset:8704
	v_add3_u32 v2, v205, v207, v204
	s_waitcnt vmcnt(8)
	ds_write_b16 v2, v16 offset:34816
	ds_write_b16_d16_hi v2, v16 offset:34960
	ds_write_b16 v2, v17 offset:35104
	ds_write_b16_d16_hi v2, v17 offset:35248
	ds_write_b16 v2, v18 offset:35392
	ds_write_b16_d16_hi v2, v18 offset:35536
	ds_write_b16 v2, v19 offset:35680
	ds_write_b16_d16_hi v2, v19 offset:35824
	v_add3_u32 v2, v191, s30, v198
	v_mov_b32_e32 v16, v1
	v_mov_b32_e32 v17, v1
	v_sub_u32_e32 v212, v2, v192
	v_mov_b32_e32 v2, v1
	v_mov_b32_e32 v4, v1
	v_mov_b32_e32 v5, v1
	v_mov_b32_e32 v6, v1
	v_mov_b32_e32 v7, v1
	v_mov_b32_e32 v8, v1
	v_mov_b32_e32 v9, v1
	v_mov_b32_e32 v10, v1
	v_mov_b32_e32 v11, v1
	v_mov_b32_e32 v12, v1
	v_mov_b32_e32 v13, v1
	v_mov_b32_e32 v14, v1
	v_mov_b32_e32 v15, v1
	v_mov_b64_e32 v[32:33], v[16:17]
	v_mov_b64_e32 v[48:49], v[16:17]
	v_mov_b64_e32 v[64:65], v[16:17]
	v_mov_b64_e32 v[30:31], v[14:15]
	v_mov_b64_e32 v[28:29], v[12:13]
	v_mov_b64_e32 v[26:27], v[10:11]
	v_mov_b64_e32 v[24:25], v[8:9]
	v_mov_b64_e32 v[22:23], v[6:7]
	v_mov_b64_e32 v[20:21], v[4:5]
	v_mov_b64_e32 v[18:19], v[2:3]
	v_mov_b64_e32 v[46:47], v[14:15]
	v_mov_b64_e32 v[44:45], v[12:13]
	v_mov_b64_e32 v[42:43], v[10:11]
	v_mov_b64_e32 v[40:41], v[8:9]
	v_mov_b64_e32 v[38:39], v[6:7]
	v_mov_b64_e32 v[36:37], v[4:5]
	v_mov_b64_e32 v[34:35], v[2:3]
	v_mov_b64_e32 v[62:63], v[14:15]
	v_mov_b64_e32 v[60:61], v[12:13]
	v_mov_b64_e32 v[58:59], v[10:11]
	v_mov_b64_e32 v[56:57], v[8:9]
	v_mov_b64_e32 v[54:55], v[6:7]
	v_mov_b64_e32 v[52:53], v[4:5]
	v_mov_b64_e32 v[50:51], v[2:3]
	s_waitcnt lgkmcnt(0)
	s_barrier
; #define LAS __attribute__((address_space(3)))
; __device__ __forceinline__ f32x16 mma32(const h16x8 a, const h16x8 b, const f32x16 c) { return __builtin_amdgcn_mfma_f32_32x32x16_f16(a, b, c, 0, 0, 0); }
; __device__ __forceinline__ void diff_attn_item(CParams& p, int j, int layer, LAS unsigned char* lds, int b, int h, int qb, int tid_in, int lane_in, int wave) {
;     ...
;     for (int kt = 0; kt < nkt; ++kt) {
;         const int k0 = kt * 64; const int cur = kt & 1;
;         const LAS h16* Ks = Ks0 + cur * 8704; const LAS h16* Vt = Vt0 + cur * 9216;
;         if (kt + 1 < nkt) ATT_STAGE(cur ^ 1, 512 + h * 128, 1024 + h * 128, kt + 2);
;         if (!(k0 > q0 + 31)) {
;         f32x16 sc[2];
; #pragma unroll
;         for (int sub = 0; sub < 2; ++sub) {
; #pragma unroll
;             for (int i = 0; i < 16; ++i) sc[sub][i] = 0.f;
; #pragma unroll
;             for (int s = 0; s < 4; ++s) sc[sub] = mma32(*(const LAS h16x8*)(Ks + (32 * sub + r) * 136 + mp * 64 + 16 * s + 8 * hh), qf[s], sc[sub]);
;         }
;         float mx = -INFINITY;
;         if (k0 + 63 + 128 <= q0) {
;             const float bfar = bdl[128];
; #pragma unroll
;             for (int sub = 0; sub < 2; ++sub)
; #pragma unroll
;                 for (int i = 0; i < 16; ++i) { sc[sub][i] += bfar; mx = fmaxf(mx, sc[sub][i]); }
;         } else {
; #pragma unroll
;             for (int sub = 0; sub < 2; ++sub)
; #pragma unroll
;                 for (int i = 0; i < 16; ++i) { const int kp = k0 + 32 * sub + (i & 3) + 8 * (i >> 2) + 4 * hh; const int dist = qp - kp;
;                     const float v = dist < 0 ? -INFINITY : sc[sub][i] + bdl[dist < 128 ? dist : 128]; sc[sub][i] = v; mx = fmaxf(mx, v); }
.LBB0_598:
	s_and_b32 s41, s38, 1
	s_xor_b32 s4, s41, 1
	s_mul_i32 s5, s4, 0x4400
	s_mulk_i32 s4, 0x4800
	s_add_i32 s6, s40, 0xffffff41
	v_add_u32_e32 v66, s4, v205
	s_add_i32 s4, s38, 2
	s_cmp_lt_u32 s38, s37
	v_add3_u32 v67, v202, s5, v203
	v_add3_u32 v68, v66, v206, v204
	s_cselect_b32 s4, s4, s39
	s_waitcnt vmcnt(3)
	ds_write_b128 v67, v[126:129]
	s_waitcnt vmcnt(2)
	ds_write_b16 v68, v118 offset:34816
	ds_write_b16_d16_hi v68, v118 offset:34960
	ds_write_b16 v68, v119 offset:35104
	ds_write_b16_d16_hi v68, v119 offset:35248
	ds_write_b16 v68, v120 offset:35392
	ds_write_b16_d16_hi v68, v120 offset:35536
	ds_write_b16 v68, v121 offset:35680
	ds_write_b16_d16_hi v68, v121 offset:35824
	s_waitcnt vmcnt(1)
	ds_write_b128 v67, v[122:125] offset:8704
	v_add3_u32 v66, v66, v207, v204
	v_lshl_add_u32 v68, s4, 6, v200
	s_waitcnt vmcnt(0)
	ds_write_b16 v66, v114 offset:34816
	ds_write_b16_d16_hi v66, v114 offset:34960
	ds_write_b16 v66, v115 offset:35104
	ds_write_b16_d16_hi v66, v115 offset:35248
	ds_write_b16 v66, v116 offset:35392
	ds_write_b16_d16_hi v66, v116 offset:35536
	ds_write_b16 v66, v117 offset:35680
	ds_write_b16_d16_hi v66, v117 offset:35824
	v_mad_i64_i32 v[66:67], s[4:5], v68, s33, v[130:131]
	global_load_dwordx4 v[126:129], v[66:67], off offset:1024
	global_load_dwordx4 v[118:121], v[66:67], off offset:2048
	v_add_u32_e32 v66, 32, v68
	v_mad_i64_i32 v[66:67], s[4:5], v66, s33, v[130:131]
	global_load_dwordx4 v[122:125], v[66:67], off offset:1024
	global_load_dwordx4 v[114:117], v[66:67], off offset:2048
	v_cmp_le_u32_e32 vcc, s6, v210
	s_and_saveexec_b64 s[4:5], vcc
	s_cbranch_execz .LBB0_670
	s_mul_i32 s6, s41, 0x4400
	v_add_u32_e32 v214, s6, v211
	ds_read_b128 v[66:69], v214 offset:0
	ds_read_b128 v[70:73], v214 offset:32
	ds_read_b128 v[74:77], v214 offset:64
	ds_read_b128 v[78:81], v214 offset:96
	ds_read_b128 v[82:85], v214 offset:8704
	ds_read_b128 v[86:89], v214 offset:8736
	ds_read_b128 v[90:93], v214 offset:8768
	ds_read_b128 v[94:97], v214 offset:8800
	s_mulk_i32 s41, 0x4800
	v_add3_u32 v215, v195, v196, s41
	v_readfirstlane_b32 s6, v199
	s_mov_b32 s7, 0x11800
	s_waitcnt lgkmcnt(4)
	v_mfma_f32_32x32x16_f16 v[162:177], v[66:69], v[110:113], 0
	v_mfma_f32_32x32x16_f16 v[162:177], v[70:73], v[106:109], v[162:177]
	v_mfma_f32_32x32x16_f16 v[162:177], v[74:77], v[102:105], v[162:177]
	v_mfma_f32_32x32x16_f16 v[162:177], v[78:81], v[98:101], v[162:177]
	s_waitcnt lgkmcnt(0)
	v_mfma_f32_32x32x16_f16 v[228:243], v[82:85], v[110:113], 0
	v_mfma_f32_32x32x16_f16 v[228:243], v[86:89], v[106:109], v[228:243]
	v_mfma_f32_32x32x16_f16 v[228:243], v[90:93], v[102:105], v[228:243]
	v_mfma_f32_32x32x16_f16 v[228:243], v[94:97], v[98:101], v[228:243]
	s_sub_u32 s6, s6, s40
	s_add_u32 s6, s6, 0xbf
	s_cmp_ge_i32 s6, 0xbf
	s_cbranch_scc1 .LdiffA_far
	s_andn2_b32 s12, s6, 32
	s_cmp_eq_u32 s12, 64
	s_cbranch_scc1 .LdiffA_mid
	s_movk_i32 s12, 0x80
	v_add_u32_e32 v66, 59, v212
	v_med3_i32 v66, v66, 0, s12
	v_lshl_add_u32 v66, v66, 2, s7
	ds_read_b32 v66, v66
	v_add_u32_e32 v67, 58, v212
	v_med3_i32 v67, v67, 0, s12
	v_lshl_add_u32 v67, v67, 2, s7
	ds_read_b32 v67, v67
	v_add_u32_e32 v68, 57, v212
	v_med3_i32 v68, v68, 0, s12
	v_lshl_add_u32 v68, v68, 2, s7
	ds_read_b32 v68, v68
	v_add_u32_e32 v69, 56, v212
	v_med3_i32 v69, v69, 0, s12
	v_lshl_add_u32 v69, v69, 2, s7
	ds_read_b32 v69, v69
	v_add_u32_e32 v70, 51, v212
	v_med3_i32 v70, v70, 0, s12
	v_lshl_add_u32 v70, v70, 2, s7
	ds_read_b32 v70, v70
	v_add_u32_e32 v71, 50, v212
	v_med3_i32 v71, v71, 0, s12
	v_lshl_add_u32 v71, v71, 2, s7
	ds_read_b32 v71, v71
	v_add_u32_e32 v72, 49, v212
	v_med3_i32 v72, v72, 0, s12
	v_lshl_add_u32 v72, v72, 2, s7
	ds_read_b32 v72, v72
	v_add_u32_e32 v73, 48, v212
	v_med3_i32 v73, v73, 0, s12
	v_lshl_add_u32 v73, v73, 2, s7
	ds_read_b32 v73, v73
	v_add_u32_e32 v74, 43, v212
	v_med3_i32 v74, v74, 0, s12
	v_lshl_add_u32 v74, v74, 2, s7
	ds_read_b32 v74, v74
	v_add_u32_e32 v75, 42, v212
	v_med3_i32 v75, v75, 0, s12
	v_lshl_add_u32 v75, v75, 2, s7
	ds_read_b32 v75, v75
	v_add_u32_e32 v76, 41, v212
	v_med3_i32 v76, v76, 0, s12
	v_lshl_add_u32 v76, v76, 2, s7
	ds_read_b32 v76, v76
	v_add_u32_e32 v77, 40, v212
	v_med3_i32 v77, v77, 0, s12
	v_lshl_add_u32 v77, v77, 2, s7
	ds_read_b32 v77, v77
	v_add_u32_e32 v78, 35, v212
	v_med3_i32 v78, v78, 0, s12
	v_lshl_add_u32 v78, v78, 2, s7
	ds_read_b32 v78, v78
	v_add_u32_e32 v79, 34, v212
	v_med3_i32 v79, v79, 0, s12
	v_lshl_add_u32 v79, v79, 2, s7
	ds_read_b32 v79, v79
	v_add_u32_e32 v80, 33, v212
	v_med3_i32 v80, v80, 0, s12
	v_lshl_add_u32 v80, v80, 2, s7
	ds_read_b32 v80, v80
	v_add_u32_e32 v81, 32, v212
	v_med3_i32 v81, v81, 0, s12
	v_lshl_add_u32 v81, v81, 2, s7
	ds_read_b32 v81, v81
	v_add_u32_e32 v82, 27, v212
	v_med3_i32 v82, v82, 0, s12
	v_lshl_add_u32 v82, v82, 2, s7
	ds_read_b32 v82, v82
	v_add_u32_e32 v83, 26, v212
	v_med3_i32 v83, v83, 0, s12
	v_lshl_add_u32 v83, v83, 2, s7
	ds_read_b32 v83, v83
	v_add_u32_e32 v84, 25, v212
	v_med3_i32 v84, v84, 0, s12
	v_lshl_add_u32 v84, v84, 2, s7
	ds_read_b32 v84, v84
	v_add_u32_e32 v85, 24, v212
	v_med3_i32 v85, v85, 0, s12
	v_lshl_add_u32 v85, v85, 2, s7
	ds_read_b32 v85, v85
	v_add_u32_e32 v86, 19, v212
	v_med3_i32 v86, v86, 0, s12
	v_lshl_add_u32 v86, v86, 2, s7
	ds_read_b32 v86, v86
	v_add_u32_e32 v87, 18, v212
	v_med3_i32 v87, v87, 0, s12
	v_lshl_add_u32 v87, v87, 2, s7
	ds_read_b32 v87, v87
	v_add_u32_e32 v88, 17, v212
	v_med3_i32 v88, v88, 0, s12
	v_lshl_add_u32 v88, v88, 2, s7
	ds_read_b32 v88, v88
	v_add_u32_e32 v89, 16, v212
	v_med3_i32 v89, v89, 0, s12
	v_lshl_add_u32 v89, v89, 2, s7
	ds_read_b32 v89, v89
	v_add_u32_e32 v90, 11, v212
	v_med3_i32 v90, v90, 0, s12
	v_lshl_add_u32 v90, v90, 2, s7
	ds_read_b32 v90, v90
	v_add_u32_e32 v91, 10, v212
	v_med3_i32 v91, v91, 0, s12
	v_lshl_add_u32 v91, v91, 2, s7
	ds_read_b32 v91, v91
	v_add_u32_e32 v92, 9, v212
	v_med3_i32 v92, v92, 0, s12
	v_lshl_add_u32 v92, v92, 2, s7
	ds_read_b32 v92, v92
	v_add_u32_e32 v93, 8, v212
	v_med3_i32 v93, v93, 0, s12
	v_lshl_add_u32 v93, v93, 2, s7
	ds_read_b32 v93, v93
	v_add_u32_e32 v94, 3, v212
	v_med3_i32 v94, v94, 0, s12
	v_lshl_add_u32 v94, v94, 2, s7
	ds_read_b32 v94, v94
	v_add_u32_e32 v95, 2, v212
	v_med3_i32 v95, v95, 0, s12
	v_lshl_add_u32 v95, v95, 2, s7
	ds_read_b32 v95, v95
	v_add_u32_e32 v96, 1, v212
	v_med3_i32 v96, v96, 0, s12
	v_lshl_add_u32 v96, v96, 2, s7
	ds_read_b32 v96, v96
	v_add_u32_e32 v97, 0, v212
	v_med3_i32 v97, v97, 0, s12
	v_lshl_add_u32 v97, v97, 2, s7
	ds_read_b32 v97, v97
	v_sub_u32_e32 v145, 0, v212
	v_mov_b32_e32 v144, 0xff800000
	s_nop 4
	s_waitcnt lgkmcnt(0)
; __device__ __forceinline__ void diff_attn_item(CParams& p, int j, int layer, LAS unsigned char* lds, int b, int h, int qb, int tid_in, int lane_in, int wave) {
;     ...
; #pragma unroll
;             for (int sub = 0; sub < 2; ++sub)
; #pragma unroll
;                 for (int i = 0; i < 16; ++i) { const int kp = k0 + 32 * sub + (i & 3) + 8 * (i >> 2) + 4 * hh; const int dist = qp - kp;
;                     const float v = dist < 0 ? -INFINITY : sc[sub][i] + bdl[dist < 128 ? dist : 128]; sc[sub][i] = v; mx = fmaxf(mx, v); }
;         }
	v_pk_add_f32 v[162:163], v[162:163], v[66:67]
	v_pk_add_f32 v[164:165], v[164:165], v[68:69]
	v_pk_add_f32 v[166:167], v[166:167], v[70:71]
	v_pk_add_f32 v[168:169], v[168:169], v[72:73]
	v_pk_add_f32 v[170:171], v[170:171], v[74:75]
	v_pk_add_f32 v[172:173], v[172:173], v[76:77]
	v_pk_add_f32 v[174:175], v[174:175], v[78:79]
	v_pk_add_f32 v[176:177], v[176:177], v[80:81]
	v_pk_add_f32 v[228:229], v[228:229], v[82:83]
	v_pk_add_f32 v[230:231], v[230:231], v[84:85]
	v_pk_add_f32 v[232:233], v[232:233], v[86:87]
	v_pk_add_f32 v[234:235], v[234:235], v[88:89]
	v_pk_add_f32 v[236:237], v[236:237], v[90:91]
	v_pk_add_f32 v[238:239], v[238:239], v[92:93]
	v_pk_add_f32 v[240:241], v[240:241], v[94:95]
	v_pk_add_f32 v[242:243], v[242:243], v[96:97]
	v_cmp_ge_i32_e64 s[46:47], 59, v145
	v_cmp_ge_i32_e64 s[48:49], 58, v145
	v_cmp_ge_i32_e64 s[50:51], 57, v145
	v_cndmask_b32_e64 v162, v144, v162, s[46:47]
	v_cmp_ge_i32_e64 s[52:53], 56, v145
	v_cndmask_b32_e64 v163, v144, v163, s[48:49]
	v_cmp_ge_i32_e64 s[46:47], 51, v145
	v_cndmask_b32_e64 v164, v144, v164, s[50:51]
	v_cmp_ge_i32_e64 s[48:49], 50, v145
	v_cndmask_b32_e64 v165, v144, v165, s[52:53]
	v_cmp_ge_i32_e64 s[50:51], 49, v145
	v_cndmask_b32_e64 v166, v144, v166, s[46:47]
	v_cmp_ge_i32_e64 s[52:53], 48, v145
	v_cndmask_b32_e64 v167, v144, v167, s[48:49]
	v_cmp_ge_i32_e64 s[46:47], 43, v145
	v_cndmask_b32_e64 v168, v144, v168, s[50:51]
	v_cmp_ge_i32_e64 s[48:49], 42, v145
	v_cndmask_b32_e64 v169, v144, v169, s[52:53]
	v_cmp_ge_i32_e64 s[50:51], 41, v145
	v_cndmask_b32_e64 v170, v144, v170, s[46:47]
	v_cmp_ge_i32_e64 s[52:53], 40, v145
	v_cndmask_b32_e64 v171, v144, v171, s[48:49]
	v_cmp_ge_i32_e64 s[46:47], 35, v145
	v_cndmask_b32_e64 v172, v144, v172, s[50:51]
	v_cmp_ge_i32_e64 s[48:49], 34, v145
	v_cndmask_b32_e64 v173, v144, v173, s[52:53]
	v_cmp_ge_i32_e64 s[50:51], 33, v145
	v_cndmask_b32_e64 v174, v144, v174, s[46:47]
	v_cmp_ge_i32_e64 s[52:53], 32, v145
	v_cndmask_b32_e64 v175, v144, v175, s[48:49]
	v_cmp_ge_i32_e64 s[46:47], 27, v145
	v_cndmask_b32_e64 v176, v144, v176, s[50:51]
	v_cmp_ge_i32_e64 s[48:49], 26, v145
	v_cndmask_b32_e64 v177, v144, v177, s[52:53]
	v_cmp_ge_i32_e64 s[50:51], 25, v145
	v_cndmask_b32_e64 v228, v144, v228, s[46:47]
	v_cmp_ge_i32_e64 s[52:53], 24, v145
	v_cndmask_b32_e64 v229, v144, v229, s[48:49]
	v_cmp_ge_i32_e64 s[46:47], 19, v145
	v_cndmask_b32_e64 v230, v144, v230, s[50:51]
	v_cmp_ge_i32_e64 s[48:49], 18, v145
	v_cndmask_b32_e64 v231, v144, v231, s[52:53]
	v_cmp_ge_i32_e64 s[50:51], 17, v145
	v_cndmask_b32_e64 v232, v144, v232, s[46:47]
	v_cmp_ge_i32_e64 s[52:53], 16, v145
	v_cndmask_b32_e64 v233, v144, v233, s[48:49]
	v_cmp_ge_i32_e64 s[46:47], 11, v145
	v_cndmask_b32_e64 v234, v144, v234, s[50:51]
	v_cmp_ge_i32_e64 s[48:49], 10, v145
	v_cndmask_b32_e64 v235, v144, v235, s[52:53]
	v_cmp_ge_i32_e64 s[50:51], 9, v145
	v_cndmask_b32_e64 v236, v144, v236, s[46:47]
	v_cmp_ge_i32_e64 s[52:53], 8, v145
	v_cndmask_b32_e64 v237, v144, v237, s[48:49]
	v_cmp_ge_i32_e64 s[46:47], 3, v145
	v_cndmask_b32_e64 v238, v144, v238, s[50:51]
	v_cmp_ge_i32_e64 s[48:49], 2, v145
	v_cndmask_b32_e64 v239, v144, v239, s[52:53]
	v_cmp_ge_i32_e64 s[50:51], 1, v145
	v_cndmask_b32_e64 v240, v144, v240, s[46:47]
	v_cmp_ge_i32_e64 s[52:53], 0, v145
	v_cndmask_b32_e64 v241, v144, v241, s[48:49]
	v_cndmask_b32_e64 v242, v144, v242, s[50:51]
	v_cndmask_b32_e64 v243, v144, v243, s[52:53]
	v_mov_b32_e32 v213, 0
	s_branch .LdiffA_max

; #define LAS __attribute__((address_space(3)))
; __device__ __forceinline__ f32x16 mma32(const h16x8 a, const h16x8 b, const f32x16 c) { return __builtin_amdgcn_mfma_f32_32x32x16_f16(a, b, c, 0, 0, 0); }
; __device__ __forceinline__ void diff_attn_item(CParams& p, int j, int layer, LAS unsigned char* lds, int b, int h, int qb, int tid_in, int lane_in, int wave) {
;     ...
;         mx = fmaxf(mx, __shfl_xor(mx, 32));
;         const float m_new = fmaxf(m_run, mx);
;         const float alpha = __builtin_amdgcn_exp2f(m_run - m_new);
;         const bool resc = __ballot(m_new > m_run) != 0ull;
;         float ls = 0.f;
; #pragma unroll
;         for (int sub = 0; sub < 2; ++sub)
; #pragma unroll
;             for (int i = 0; i < 16; ++i) { const float e = __builtin_amdgcn_exp2f(sc[sub][i] - m_new); sc[sub][i] = e; ls += e; }
;         ls += __shfl_xor(ls, 32);
;         l_run = l_run * alpha + ls; m_run = m_new;
;         if (resc) {
; #pragma unroll
;             for (int d = 0; d < 4; ++d)
; #pragma unroll
;                 for (int i = 0; i < 16; ++i) o[d][i] *= alpha;
;         }
; #pragma unroll
;         for (int sub = 0; sub < 2; ++sub)
; #pragma unroll
;             for (int s2 = 0; s2 < 2; ++s2) {
;                 h16x8 pf;
; #pragma unroll
;                 for (int jj = 0; jj < 8; ++jj) pf[jj] = (h16)sc[sub][8 * s2 + jj];
; #pragma unroll
;                 for (int d = 0; d < 4; ++d) {
;                     const int coff = 32 * d * 72 + ((((sub << 1) | s2) ^ d) << 4);
;                     const h16x4 lo = *(const LAS h16x4*)(Vt + vlo + coff), hi = *(const LAS h16x4*)(Vt + vhi + coff);
;                     h16x8 vf; vf[0] = lo[0]; vf[1] = lo[1]; vf[2] = lo[2]; vf[3] = lo[3]; vf[4] = hi[0]; vf[5] = hi[1]; vf[6] = hi[2]; vf[7] = hi[3];
;                     o[d] = mma32(vf, pf, o[d]);
.LdiffA_max:
	v_max3_f32 v249, v162, v163, v164
	v_max3_f32 v249, v249, v165, v166
	v_max3_f32 v249, v249, v167, v168
	v_max3_f32 v249, v249, v169, v170
	v_max3_f32 v249, v249, v171, v172
	v_max3_f32 v249, v249, v173, v174
	v_max3_f32 v249, v249, v175, v176
	v_max3_f32 v249, v249, v177, v228
	v_max3_f32 v249, v249, v229, v230
	v_max3_f32 v249, v249, v231, v232
	v_max3_f32 v249, v249, v233, v234
	v_max3_f32 v249, v249, v235, v236
	v_max3_f32 v249, v249, v237, v238
	v_max3_f32 v249, v249, v239, v240
	v_max3_f32 v249, v249, v241, v242
	v_max_f32_e32 v249, v249, v243
	s_waitcnt lgkmcnt(0)
	v_add_f32_e32 v249, v249, v213
	ds_bpermute_b32 v251, v185, v249
	s_waitcnt lgkmcnt(0)
	v_max3_f32 v248, v201, v249, v251
	v_sub_f32_e32 v244, v201, v248
	v_exp_f32_e32 v244, v244
	v_cmp_gt_f32_e32 vcc, v248, v201
	v_sub_f32_e32 v246, v248, v213
	v_mov_b32_e32 v201, v248
	v_pk_add_f32 v[162:163], v[162:163], v[246:247] op_sel_hi:[1,0] neg_lo:[0,1] neg_hi:[0,1]
	v_pk_add_f32 v[164:165], v[164:165], v[246:247] op_sel_hi:[1,0] neg_lo:[0,1] neg_hi:[0,1]
	v_pk_add_f32 v[166:167], v[166:167], v[246:247] op_sel_hi:[1,0] neg_lo:[0,1] neg_hi:[0,1]
	v_pk_add_f32 v[168:169], v[168:169], v[246:247] op_sel_hi:[1,0] neg_lo:[0,1] neg_hi:[0,1]
	v_pk_add_f32 v[170:171], v[170:171], v[246:247] op_sel_hi:[1,0] neg_lo:[0,1] neg_hi:[0,1]
	v_pk_add_f32 v[172:173], v[172:173], v[246:247] op_sel_hi:[1,0] neg_lo:[0,1] neg_hi:[0,1]
	v_pk_add_f32 v[174:175], v[174:175], v[246:247] op_sel_hi:[1,0] neg_lo:[0,1] neg_hi:[0,1]
	v_pk_add_f32 v[176:177], v[176:177], v[246:247] op_sel_hi:[1,0] neg_lo:[0,1] neg_hi:[0,1]
	v_pk_add_f32 v[228:229], v[228:229], v[246:247] op_sel_hi:[1,0] neg_lo:[0,1] neg_hi:[0,1]
	v_pk_add_f32 v[230:231], v[230:231], v[246:247] op_sel_hi:[1,0] neg_lo:[0,1] neg_hi:[0,1]
	v_pk_add_f32 v[232:233], v[232:233], v[246:247] op_sel_hi:[1,0] neg_lo:[0,1] neg_hi:[0,1]
	v_pk_add_f32 v[234:235], v[234:235], v[246:247] op_sel_hi:[1,0] neg_lo:[0,1] neg_hi:[0,1]
	v_pk_add_f32 v[236:237], v[236:237], v[246:247] op_sel_hi:[1,0] neg_lo:[0,1] neg_hi:[0,1]
	v_pk_add_f32 v[238:239], v[238:239], v[246:247] op_sel_hi:[1,0] neg_lo:[0,1] neg_hi:[0,1]
	v_pk_add_f32 v[240:241], v[240:241], v[246:247] op_sel_hi:[1,0] neg_lo:[0,1] neg_hi:[0,1]
	v_pk_add_f32 v[242:243], v[242:243], v[246:247] op_sel_hi:[1,0] neg_lo:[0,1] neg_hi:[0,1]
	v_exp_f32_e32 v162, v162
	v_exp_f32_e32 v163, v163
	v_exp_f32_e32 v164, v164
	v_exp_f32_e32 v165, v165
	v_exp_f32_e32 v166, v166
	v_exp_f32_e32 v167, v167
	v_exp_f32_e32 v168, v168
	v_exp_f32_e32 v169, v169
	v_exp_f32_e32 v170, v170
	v_exp_f32_e32 v171, v171
	v_exp_f32_e32 v172, v172
	v_exp_f32_e32 v173, v173
	v_exp_f32_e32 v174, v174
	v_exp_f32_e32 v175, v175
	v_exp_f32_e32 v176, v176
	v_exp_f32_e32 v177, v177
	v_exp_f32_e32 v228, v228
	v_exp_f32_e32 v229, v229
	v_exp_f32_e32 v230, v230
	v_exp_f32_e32 v231, v231
	v_exp_f32_e32 v232, v232
	v_exp_f32_e32 v233, v233
	v_exp_f32_e32 v234, v234
	v_exp_f32_e32 v235, v235
	v_exp_f32_e32 v236, v236
	v_exp_f32_e32 v237, v237
	v_exp_f32_e32 v238, v238
	v_exp_f32_e32 v239, v239
	v_exp_f32_e32 v240, v240
	v_exp_f32_e32 v241, v241
	v_exp_f32_e32 v242, v242
	v_exp_f32_e32 v243, v243
	v_pk_add_f32 v[250:251], v[162:163], v[164:165]
	v_pk_add_f32 v[250:251], v[250:251], v[166:167]
	v_pk_add_f32 v[250:251], v[250:251], v[168:169]
	v_pk_add_f32 v[250:251], v[250:251], v[170:171]
	v_pk_add_f32 v[250:251], v[250:251], v[172:173]
	v_pk_add_f32 v[250:251], v[250:251], v[174:175]
	v_pk_add_f32 v[250:251], v[250:251], v[176:177]
	v_pk_add_f32 v[250:251], v[250:251], v[228:229]
	v_pk_add_f32 v[250:251], v[250:251], v[230:231]
	v_pk_add_f32 v[250:251], v[250:251], v[232:233]
	v_pk_add_f32 v[250:251], v[250:251], v[234:235]
	v_pk_add_f32 v[250:251], v[250:251], v[236:237]
	v_pk_add_f32 v[250:251], v[250:251], v[238:239]
	v_pk_add_f32 v[250:251], v[250:251], v[240:241]
	v_pk_add_f32 v[250:251], v[250:251], v[242:243]
	s_nop 0
	v_add_f32_e32 v250, v250, v251
	ds_bpermute_b32 v251, v185, v250
	v_cvt_pk_f16_f32 v144, v162, v163
	v_cvt_pk_f16_f32 v145, v164, v165
	v_cvt_pk_f16_f32 v146, v166, v167
	v_cvt_pk_f16_f32 v147, v168, v169
	v_cvt_pk_f16_f32 v148, v170, v171
	v_cvt_pk_f16_f32 v149, v172, v173
	v_cvt_pk_f16_f32 v150, v174, v175
	v_cvt_pk_f16_f32 v151, v176, v177
	v_cvt_pk_f16_f32 v152, v228, v229
	v_cvt_pk_f16_f32 v153, v230, v231
	v_cvt_pk_f16_f32 v154, v232, v233
	v_cvt_pk_f16_f32 v155, v234, v235
	v_cvt_pk_f16_f32 v178, v236, v237
	v_cvt_pk_f16_f32 v179, v238, v239
	v_cvt_pk_f16_f32 v180, v240, v241
	v_cvt_pk_f16_f32 v181, v242, v243
	s_waitcnt lgkmcnt(0)
	v_add_f32_e32 v250, v250, v251
	v_fma_f32 v197, v197, v244, v250
	ds_read_b128 v[66:69], v215 offset:34816
	ds_read_b128 v[70:73], v215 offset:39456
	ds_read_b128 v[74:77], v215 offset:44096
	ds_read_b128 v[78:81], v215 offset:48736
	s_cbranch_vccz .LdiffA_noresc
	v_pk_mul_f32 v[50:51], v[50:51], v[244:245] op_sel_hi:[1,0]
	v_pk_mul_f32 v[52:53], v[52:53], v[244:245] op_sel_hi:[1,0]
	v_pk_mul_f32 v[54:55], v[54:55], v[244:245] op_sel_hi:[1,0]
	v_pk_mul_f32 v[56:57], v[56:57], v[244:245] op_sel_hi:[1,0]
	v_pk_mul_f32 v[58:59], v[58:59], v[244:245] op_sel_hi:[1,0]
	v_pk_mul_f32 v[60:61], v[60:61], v[244:245] op_sel_hi:[1,0]
	v_pk_mul_f32 v[62:63], v[62:63], v[244:245] op_sel_hi:[1,0]
	v_pk_mul_f32 v[64:65], v[64:65], v[244:245] op_sel_hi:[1,0]
	v_pk_mul_f32 v[34:35], v[34:35], v[244:245] op_sel_hi:[1,0]
	v_pk_mul_f32 v[36:37], v[36:37], v[244:245] op_sel_hi:[1,0]
	v_pk_mul_f32 v[38:39], v[38:39], v[244:245] op_sel_hi:[1,0]
	v_pk_mul_f32 v[40:41], v[40:41], v[244:245] op_sel_hi:[1,0]
	v_pk_mul_f32 v[42:43], v[42:43], v[244:245] op_sel_hi:[1,0]
	v_pk_mul_f32 v[44:45], v[44:45], v[244:245] op_sel_hi:[1,0]
	v_pk_mul_f32 v[46:47], v[46:47], v[244:245] op_sel_hi:[1,0]
	v_pk_mul_f32 v[48:49], v[48:49], v[244:245] op_sel_hi:[1,0]
	v_pk_mul_f32 v[18:19], v[18:19], v[244:245] op_sel_hi:[1,0]
	v_pk_mul_f32 v[20:21], v[20:21], v[244:245] op_sel_hi:[1,0]
	v_pk_mul_f32 v[22:23], v[22:23], v[244:245] op_sel_hi:[1,0]
	v_pk_mul_f32 v[24:25], v[24:25], v[244:245] op_sel_hi:[1,0]
	v_pk_mul_f32 v[26:27], v[26:27], v[244:245] op_sel_hi:[1,0]
	v_pk_mul_f32 v[28:29], v[28:29], v[244:245] op_sel_hi:[1,0]
	v_pk_mul_f32 v[30:31], v[30:31], v[244:245] op_sel_hi:[1,0]
	v_pk_mul_f32 v[32:33], v[32:33], v[244:245] op_sel_hi:[1,0]
	v_pk_mul_f32 v[2:3], v[2:3], v[244:245] op_sel_hi:[1,0]
	v_pk_mul_f32 v[4:5], v[4:5], v[244:245] op_sel_hi:[1,0]
	v_pk_mul_f32 v[6:7], v[6:7], v[244:245] op_sel_hi:[1,0]
	v_pk_mul_f32 v[8:9], v[8:9], v[244:245] op_sel_hi:[1,0]
	v_pk_mul_f32 v[10:11], v[10:11], v[244:245] op_sel_hi:[1,0]
	v_pk_mul_f32 v[12:13], v[12:13], v[244:245] op_sel_hi:[1,0]
	v_pk_mul_f32 v[14:15], v[14:15], v[244:245] op_sel_hi:[1,0]
	v_pk_mul_f32 v[16:17], v[16:17], v[244:245] op_sel_hi:[1,0]
; #define LAS __attribute__((address_space(3)))
; __device__ __forceinline__ f32x16 mma32(const h16x8 a, const h16x8 b, const f32x16 c) { return __builtin_amdgcn_mfma_f32_32x32x16_f16(a, b, c, 0, 0, 0); }
; __device__ __forceinline__ void diff_attn_item(CParams& p, int j, int layer, LAS unsigned char* lds, int b, int h, int qb, int tid_in, int lane_in, int wave) {
;     ...
; #pragma unroll
;         for (int sub = 0; sub < 2; ++sub)
; #pragma unroll
;             for (int s2 = 0; s2 < 2; ++s2) {
;                 h16x8 pf;
; #pragma unroll
;                 for (int jj = 0; jj < 8; ++jj) pf[jj] = (h16)sc[sub][8 * s2 + jj];
; #pragma unroll
;                 for (int d = 0; d < 4; ++d) {
;                     const int coff = 32 * d * 72 + ((((sub << 1) | s2) ^ d) << 4);
;                     const h16x4 lo = *(const LAS h16x4*)(Vt + vlo + coff), hi = *(const LAS h16x4*)(Vt + vhi + coff);
;                     h16x8 vf; vf[0] = lo[0]; vf[1] = lo[1]; vf[2] = lo[2]; vf[3] = lo[3]; vf[4] = hi[0]; vf[5] = hi[1]; vf[6] = hi[2]; vf[7] = hi[3];
;                     o[d] = mma32(vf, pf, o[d]);
;                 }
;             }
.LdiffA_noresc:
	ds_read_b128 v[82:85], v215 offset:34848
	ds_read_b128 v[86:89], v215 offset:39424
	ds_read_b128 v[90:93], v215 offset:44128
	ds_read_b128 v[94:97], v215 offset:48704
	s_waitcnt lgkmcnt(4)
	v_mfma_f32_32x32x16_f16 v[50:65], v[66:69], v[144:147], v[50:65]
	v_mfma_f32_32x32x16_f16 v[34:49], v[70:73], v[144:147], v[34:49]
	v_mfma_f32_32x32x16_f16 v[18:33], v[74:77], v[144:147], v[18:33]
	v_mfma_f32_32x32x16_f16 v[2:17], v[78:81], v[144:147], v[2:17]
	ds_read_b128 v[66:69], v215 offset:34880
	ds_read_b128 v[70:73], v215 offset:39520
	ds_read_b128 v[74:77], v215 offset:44032
	ds_read_b128 v[78:81], v215 offset:48672
	s_waitcnt lgkmcnt(4)
	v_mfma_f32_32x32x16_f16 v[50:65], v[82:85], v[148:151], v[50:65]
	v_mfma_f32_32x32x16_f16 v[34:49], v[86:89], v[148:151], v[34:49]
	v_mfma_f32_32x32x16_f16 v[18:33], v[90:93], v[148:151], v[18:33]
	v_mfma_f32_32x32x16_f16 v[2:17], v[94:97], v[148:151], v[2:17]
	ds_read_b128 v[82:85], v215 offset:34912
	ds_read_b128 v[86:89], v215 offset:39488
	ds_read_b128 v[90:93], v215 offset:44064
	ds_read_b128 v[94:97], v215 offset:48640
	s_waitcnt lgkmcnt(4)
	v_mfma_f32_32x32x16_f16 v[50:65], v[66:69], v[152:155], v[50:65]
	v_mfma_f32_32x32x16_f16 v[34:49], v[70:73], v[152:155], v[34:49]
	v_mfma_f32_32x32x16_f16 v[18:33], v[74:77], v[152:155], v[18:33]
	v_mfma_f32_32x32x16_f16 v[2:17], v[78:81], v[152:155], v[2:17]
	s_waitcnt lgkmcnt(0)
	v_mfma_f32_32x32x16_f16 v[50:65], v[82:85], v[178:181], v[50:65]
	v_mfma_f32_32x32x16_f16 v[34:49], v[86:89], v[178:181], v[34:49]
	v_mfma_f32_32x32x16_f16 v[18:33], v[90:93], v[178:181], v[18:33]
	v_mfma_f32_32x32x16_f16 v[2:17], v[94:97], v[178:181], v[2:17]

; #define LAS __attribute__((address_space(3)))
; __device__ __forceinline__ f32x16 mma32(const h16x8 a, const h16x8 b, const f32x16 c) { return __builtin_amdgcn_mfma_f32_32x32x16_f16(a, b, c, 0, 0, 0); }
; __device__ __forceinline__ void diff_attn_item(CParams& p, int j, int layer, LAS unsigned char* lds, int b, int h, int qb, int tid_in, int lane_in, int wave) {
;     ...
;     for (int kt = 0; kt < nkt; ++kt) {
;         const int k0 = kt * 64; const int cur = kt & 1;
;         const LAS h16* Ks = Ks0 + cur * 8704; const LAS h16* Vt = Vt0 + cur * 9216;
;         if (kt + 1 < nkt) ATT_STAGE(cur ^ 1, 512 + h * 128, 1024 + h * 128, kt + 2);
;         if (!(k0 > q0 + 31)) {
;         f32x16 sc[2];
; #pragma unroll
;         for (int sub = 0; sub < 2; ++sub) {
; #pragma unroll
;             for (int i = 0; i < 16; ++i) sc[sub][i] = 0.f;
; #pragma unroll
;             for (int s = 0; s < 4; ++s) sc[sub] = mma32(*(const LAS h16x8*)(Ks + (32 * sub + r) * 136 + mp * 64 + 16 * s + 8 * hh), qf[s], sc[sub]);
;         }
;         float mx = -INFINITY;
;         if (k0 + 63 + 128 <= q0) {
;             const float bfar = bdl[128];
; #pragma unroll
;             for (int sub = 0; sub < 2; ++sub)
; #pragma unroll
;                 for (int i = 0; i < 16; ++i) { sc[sub][i] += bfar; mx = fmaxf(mx, sc[sub][i]); }
;         } else {
; #pragma unroll
;             for (int sub = 0; sub < 2; ++sub)
; #pragma unroll
;                 for (int i = 0; i < 16; ++i) { const int kp = k0 + 32 * sub + (i & 3) + 8 * (i >> 2) + 4 * hh; const int dist = qp - kp;
;                     const float v = dist < 0 ? -INFINITY : sc[sub][i] + bdl[dist < 128 ? dist : 128]; sc[sub][i] = v; mx = fmaxf(mx, v); }
.LBB0_672:
	s_lshl_b32 s30, s12, 6
	v_cmp_le_u32_e32 vcc, s30, v210
	s_and_saveexec_b64 s[4:5], vcc
	s_cbranch_execz .LBB0_744
	s_and_b32 s41, s12, 1
	s_waitcnt vmcnt(0)
	s_mul_i32 s6, s41, 0x4400
	v_add_u32_e32 v214, s6, v211
	ds_read_b128 v[66:69], v214 offset:0
	ds_read_b128 v[70:73], v214 offset:32
	ds_read_b128 v[74:77], v214 offset:64
	ds_read_b128 v[78:81], v214 offset:96
	ds_read_b128 v[82:85], v214 offset:8704
	ds_read_b128 v[86:89], v214 offset:8736
	ds_read_b128 v[90:93], v214 offset:8768
	ds_read_b128 v[94:97], v214 offset:8800
	s_mulk_i32 s41, 0x4800
	v_add3_u32 v215, v195, v196, s41
	v_readfirstlane_b32 s6, v199
	s_mov_b32 s7, 0x11800
	s_waitcnt lgkmcnt(4)
	v_mfma_f32_32x32x16_f16 v[162:177], v[66:69], v[110:113], 0
	v_mfma_f32_32x32x16_f16 v[162:177], v[70:73], v[106:109], v[162:177]
	v_mfma_f32_32x32x16_f16 v[162:177], v[74:77], v[102:105], v[162:177]
	v_mfma_f32_32x32x16_f16 v[162:177], v[78:81], v[98:101], v[162:177]
	s_waitcnt lgkmcnt(0)
	v_mfma_f32_32x32x16_f16 v[228:243], v[82:85], v[110:113], 0
	v_mfma_f32_32x32x16_f16 v[228:243], v[86:89], v[106:109], v[228:243]
	v_mfma_f32_32x32x16_f16 v[228:243], v[90:93], v[102:105], v[228:243]
	v_mfma_f32_32x32x16_f16 v[228:243], v[94:97], v[98:101], v[228:243]
	s_sub_u32 s6, s6, s40
	s_add_u32 s6, s6, 0xbf
	s_cmp_ge_i32 s6, 0xbf
	s_cbranch_scc1 .LdiffB_far
	s_andn2_b32 s12, s6, 32
	s_cmp_eq_u32 s12, 64
	s_cbranch_scc1 .LdiffB_mid
	s_movk_i32 s12, 0x80
	v_add_u32_e32 v66, 59, v212
	v_med3_i32 v66, v66, 0, s12
	v_lshl_add_u32 v66, v66, 2, s7
	ds_read_b32 v66, v66
	v_add_u32_e32 v67, 58, v212
	v_med3_i32 v67, v67, 0, s12
	v_lshl_add_u32 v67, v67, 2, s7
	ds_read_b32 v67, v67
	v_add_u32_e32 v68, 57, v212
	v_med3_i32 v68, v68, 0, s12
	v_lshl_add_u32 v68, v68, 2, s7
	ds_read_b32 v68, v68
	v_add_u32_e32 v69, 56, v212
	v_med3_i32 v69, v69, 0, s12
	v_lshl_add_u32 v69, v69, 2, s7
	ds_read_b32 v69, v69
	v_add_u32_e32 v70, 51, v212
	v_med3_i32 v70, v70, 0, s12
	v_lshl_add_u32 v70, v70, 2, s7
	ds_read_b32 v70, v70
	v_add_u32_e32 v71, 50, v212
	v_med3_i32 v71, v71, 0, s12
	v_lshl_add_u32 v71, v71, 2, s7
	ds_read_b32 v71, v71
	v_add_u32_e32 v72, 49, v212
	v_med3_i32 v72, v72, 0, s12
	v_lshl_add_u32 v72, v72, 2, s7
	ds_read_b32 v72, v72
	v_add_u32_e32 v73, 48, v212
	v_med3_i32 v73, v73, 0, s12
	v_lshl_add_u32 v73, v73, 2, s7
	ds_read_b32 v73, v73
	v_add_u32_e32 v74, 43, v212
	v_med3_i32 v74, v74, 0, s12
	v_lshl_add_u32 v74, v74, 2, s7
	ds_read_b32 v74, v74
	v_add_u32_e32 v75, 42, v212
	v_med3_i32 v75, v75, 0, s12
	v_lshl_add_u32 v75, v75, 2, s7
	ds_read_b32 v75, v75
	v_add_u32_e32 v76, 41, v212
	v_med3_i32 v76, v76, 0, s12
	v_lshl_add_u32 v76, v76, 2, s7
	ds_read_b32 v76, v76
	v_add_u32_e32 v77, 40, v212
	v_med3_i32 v77, v77, 0, s12
	v_lshl_add_u32 v77, v77, 2, s7
	ds_read_b32 v77, v77
	v_add_u32_e32 v78, 35, v212
	v_med3_i32 v78, v78, 0, s12
	v_lshl_add_u32 v78, v78, 2, s7
	ds_read_b32 v78, v78
	v_add_u32_e32 v79, 34, v212
	v_med3_i32 v79, v79, 0, s12
	v_lshl_add_u32 v79, v79, 2, s7
	ds_read_b32 v79, v79
	v_add_u32_e32 v80, 33, v212
	v_med3_i32 v80, v80, 0, s12
	v_lshl_add_u32 v80, v80, 2, s7
	ds_read_b32 v80, v80
	v_add_u32_e32 v81, 32, v212
	v_med3_i32 v81, v81, 0, s12
	v_lshl_add_u32 v81, v81, 2, s7
	ds_read_b32 v81, v81
	v_add_u32_e32 v82, 27, v212
	v_med3_i32 v82, v82, 0, s12
	v_lshl_add_u32 v82, v82, 2, s7
	ds_read_b32 v82, v82
	v_add_u32_e32 v83, 26, v212
	v_med3_i32 v83, v83, 0, s12
	v_lshl_add_u32 v83, v83, 2, s7
	ds_read_b32 v83, v83
	v_add_u32_e32 v84, 25, v212
	v_med3_i32 v84, v84, 0, s12
	v_lshl_add_u32 v84, v84, 2, s7
	ds_read_b32 v84, v84
	v_add_u32_e32 v85, 24, v212
	v_med3_i32 v85, v85, 0, s12
	v_lshl_add_u32 v85, v85, 2, s7
	ds_read_b32 v85, v85
	v_add_u32_e32 v86, 19, v212
	v_med3_i32 v86, v86, 0, s12
	v_lshl_add_u32 v86, v86, 2, s7
	ds_read_b32 v86, v86
	v_add_u32_e32 v87, 18, v212
	v_med3_i32 v87, v87, 0, s12
	v_lshl_add_u32 v87, v87, 2, s7
	ds_read_b32 v87, v87
	v_add_u32_e32 v88, 17, v212
	v_med3_i32 v88, v88, 0, s12
	v_lshl_add_u32 v88, v88, 2, s7
	ds_read_b32 v88, v88
	v_add_u32_e32 v89, 16, v212
	v_med3_i32 v89, v89, 0, s12
	v_lshl_add_u32 v89, v89, 2, s7
	ds_read_b32 v89, v89
	v_add_u32_e32 v90, 11, v212
	v_med3_i32 v90, v90, 0, s12
	v_lshl_add_u32 v90, v90, 2, s7
	ds_read_b32 v90, v90
	v_add_u32_e32 v91, 10, v212
	v_med3_i32 v91, v91, 0, s12
	v_lshl_add_u32 v91, v91, 2, s7
	ds_read_b32 v91, v91
	v_add_u32_e32 v92, 9, v212
	v_med3_i32 v92, v92, 0, s12
	v_lshl_add_u32 v92, v92, 2, s7
	ds_read_b32 v92, v92
	v_add_u32_e32 v93, 8, v212
	v_med3_i32 v93, v93, 0, s12
	v_lshl_add_u32 v93, v93, 2, s7
	ds_read_b32 v93, v93
	v_add_u32_e32 v94, 3, v212
	v_med3_i32 v94, v94, 0, s12
	v_lshl_add_u32 v94, v94, 2, s7
	ds_read_b32 v94, v94
	v_add_u32_e32 v95, 2, v212
	v_med3_i32 v95, v95, 0, s12
	v_lshl_add_u32 v95, v95, 2, s7
	ds_read_b32 v95, v95
	v_add_u32_e32 v96, 1, v212
	v_med3_i32 v96, v96, 0, s12
	v_lshl_add_u32 v96, v96, 2, s7
	ds_read_b32 v96, v96
	v_add_u32_e32 v97, 0, v212
	v_med3_i32 v97, v97, 0, s12
	v_lshl_add_u32 v97, v97, 2, s7
	ds_read_b32 v97, v97
	v_sub_u32_e32 v145, 0, v212
	v_mov_b32_e32 v144, 0xff800000
	s_nop 4
	s_waitcnt lgkmcnt(0)
; __device__ __forceinline__ void diff_attn_item(CParams& p, int j, int layer, LAS unsigned char* lds, int b, int h, int qb, int tid_in, int lane_in, int wave) {
;     ...
; #pragma unroll
;             for (int sub = 0; sub < 2; ++sub)
; #pragma unroll
;                 for (int i = 0; i < 16; ++i) { const int kp = k0 + 32 * sub + (i & 3) + 8 * (i >> 2) + 4 * hh; const int dist = qp - kp;
;                     const float v = dist < 0 ? -INFINITY : sc[sub][i] + bdl[dist < 128 ? dist : 128]; sc[sub][i] = v; mx = fmaxf(mx, v); }
;         }
	v_pk_add_f32 v[162:163], v[162:163], v[66:67]
	v_pk_add_f32 v[164:165], v[164:165], v[68:69]
	v_pk_add_f32 v[166:167], v[166:167], v[70:71]
	v_pk_add_f32 v[168:169], v[168:169], v[72:73]
	v_pk_add_f32 v[170:171], v[170:171], v[74:75]
	v_pk_add_f32 v[172:173], v[172:173], v[76:77]
	v_pk_add_f32 v[174:175], v[174:175], v[78:79]
	v_pk_add_f32 v[176:177], v[176:177], v[80:81]
	v_pk_add_f32 v[228:229], v[228:229], v[82:83]
	v_pk_add_f32 v[230:231], v[230:231], v[84:85]
	v_pk_add_f32 v[232:233], v[232:233], v[86:87]
	v_pk_add_f32 v[234:235], v[234:235], v[88:89]
	v_pk_add_f32 v[236:237], v[236:237], v[90:91]
	v_pk_add_f32 v[238:239], v[238:239], v[92:93]
	v_pk_add_f32 v[240:241], v[240:241], v[94:95]
	v_pk_add_f32 v[242:243], v[242:243], v[96:97]
	v_cmp_ge_i32_e64 s[46:47], 59, v145
	v_cmp_ge_i32_e64 s[48:49], 58, v145
	v_cmp_ge_i32_e64 s[50:51], 57, v145
	v_cndmask_b32_e64 v162, v144, v162, s[46:47]
	v_cmp_ge_i32_e64 s[52:53], 56, v145
	v_cndmask_b32_e64 v163, v144, v163, s[48:49]
	v_cmp_ge_i32_e64 s[46:47], 51, v145
	v_cndmask_b32_e64 v164, v144, v164, s[50:51]
	v_cmp_ge_i32_e64 s[48:49], 50, v145
	v_cndmask_b32_e64 v165, v144, v165, s[52:53]
	v_cmp_ge_i32_e64 s[50:51], 49, v145
	v_cndmask_b32_e64 v166, v144, v166, s[46:47]
	v_cmp_ge_i32_e64 s[52:53], 48, v145
	v_cndmask_b32_e64 v167, v144, v167, s[48:49]
	v_cmp_ge_i32_e64 s[46:47], 43, v145
	v_cndmask_b32_e64 v168, v144, v168, s[50:51]
	v_cmp_ge_i32_e64 s[48:49], 42, v145
	v_cndmask_b32_e64 v169, v144, v169, s[52:53]
	v_cmp_ge_i32_e64 s[50:51], 41, v145
	v_cndmask_b32_e64 v170, v144, v170, s[46:47]
	v_cmp_ge_i32_e64 s[52:53], 40, v145
	v_cndmask_b32_e64 v171, v144, v171, s[48:49]
	v_cmp_ge_i32_e64 s[46:47], 35, v145
	v_cndmask_b32_e64 v172, v144, v172, s[50:51]
	v_cmp_ge_i32_e64 s[48:49], 34, v145
	v_cndmask_b32_e64 v173, v144, v173, s[52:53]
	v_cmp_ge_i32_e64 s[50:51], 33, v145
	v_cndmask_b32_e64 v174, v144, v174, s[46:47]
	v_cmp_ge_i32_e64 s[52:53], 32, v145
	v_cndmask_b32_e64 v175, v144, v175, s[48:49]
	v_cmp_ge_i32_e64 s[46:47], 27, v145
	v_cndmask_b32_e64 v176, v144, v176, s[50:51]
	v_cmp_ge_i32_e64 s[48:49], 26, v145
	v_cndmask_b32_e64 v177, v144, v177, s[52:53]
	v_cmp_ge_i32_e64 s[50:51], 25, v145
	v_cndmask_b32_e64 v228, v144, v228, s[46:47]
	v_cmp_ge_i32_e64 s[52:53], 24, v145
	v_cndmask_b32_e64 v229, v144, v229, s[48:49]
	v_cmp_ge_i32_e64 s[46:47], 19, v145
	v_cndmask_b32_e64 v230, v144, v230, s[50:51]
	v_cmp_ge_i32_e64 s[48:49], 18, v145
	v_cndmask_b32_e64 v231, v144, v231, s[52:53]
	v_cmp_ge_i32_e64 s[50:51], 17, v145
	v_cndmask_b32_e64 v232, v144, v232, s[46:47]
	v_cmp_ge_i32_e64 s[52:53], 16, v145
	v_cndmask_b32_e64 v233, v144, v233, s[48:49]
	v_cmp_ge_i32_e64 s[46:47], 11, v145
	v_cndmask_b32_e64 v234, v144, v234, s[50:51]
	v_cmp_ge_i32_e64 s[48:49], 10, v145
	v_cndmask_b32_e64 v235, v144, v235, s[52:53]
	v_cmp_ge_i32_e64 s[50:51], 9, v145
	v_cndmask_b32_e64 v236, v144, v236, s[46:47]
	v_cmp_ge_i32_e64 s[52:53], 8, v145
	v_cndmask_b32_e64 v237, v144, v237, s[48:49]
	v_cmp_ge_i32_e64 s[46:47], 3, v145
	v_cndmask_b32_e64 v238, v144, v238, s[50:51]
	v_cmp_ge_i32_e64 s[48:49], 2, v145
	v_cndmask_b32_e64 v239, v144, v239, s[52:53]
	v_cmp_ge_i32_e64 s[50:51], 1, v145
	v_cndmask_b32_e64 v240, v144, v240, s[46:47]
	v_cmp_ge_i32_e64 s[52:53], 0, v145
	v_cndmask_b32_e64 v241, v144, v241, s[48:49]
	v_cndmask_b32_e64 v242, v144, v242, s[50:51]
	v_cndmask_b32_e64 v243, v144, v243, s[52:53]
	v_mov_b32_e32 v213, 0
	s_branch .LdiffB_max
